# lever 8 variant: LDS read-ahead distance 8 in the scan phases 7 and 14
# baseline (speedup 1.0000x reference)
.LBB0_1046:
	v_mov_b32_e32 v37, v34
	v_mov_b32_e32 v34, v33
	v_mov_b32_e32 v36, v32
	v_pk_mul_f32 v[32:33], v[80:81], v[34:35]
	v_mov_b32_e32 v34, v38
	v_mov_b32_e32 v35, v40
	v_pk_mul_f32 v[36:37], v[80:81], v[36:37]
	v_pk_mul_f32 v[34:35], v[80:81], v[34:35]
	v_cvt_pk_bf16_f32 v36, v36, v37
	v_mov_b32_e32 v40, v39
	v_cvt_pk_bf16_f32 v37, v34, v35
	v_mov_b32_e32 v34, v42
	v_mov_b32_e32 v35, v44
	v_mov_b32_e32 v44, v43
	v_pk_mul_f32 v[38:39], v[80:81], v[40:41]
	v_pk_mul_f32 v[34:35], v[80:81], v[34:35]
	v_pk_mul_f32 v[40:41], v[80:81], v[44:45]
	v_cvt_pk_bf16_f32 v32, v32, v33
	v_cvt_pk_bf16_f32 v33, v38, v39
	v_cvt_pk_bf16_f32 v38, v34, v35
	v_cvt_pk_bf16_f32 v34, v40, v41
	v_mov_b32_e32 v40, v46
	v_mov_b32_e32 v41, v48
	v_pk_mul_f32 v[40:41], v[80:81], v[40:41]
	v_mov_b32_e32 v48, v47
	v_pk_mul_f32 v[42:43], v[80:81], v[48:49]
	v_cvt_pk_bf16_f32 v39, v40, v41
	v_mov_b32_e32 v40, v50
	v_mov_b32_e32 v41, v52
	v_mov_b32_e32 v52, v51
	v_cvt_pk_bf16_f32 v35, v42, v43
	v_pk_mul_f32 v[40:41], v[80:81], v[40:41]
	v_pk_mul_f32 v[42:43], v[80:81], v[52:53]
	v_cvt_pk_bf16_f32 v44, v40, v41
	v_cvt_pk_bf16_f32 v40, v42, v43
	v_mov_b32_e32 v42, v54
	v_mov_b32_e32 v43, v56
	v_pk_mul_f32 v[42:43], v[80:81], v[42:43]
	v_mov_b32_e32 v56, v55
	v_cvt_pk_bf16_f32 v45, v42, v43
	v_mov_b32_e32 v42, v58
	v_mov_b32_e32 v43, v60
	v_mov_b32_e32 v60, v59
	v_pk_mul_f32 v[46:47], v[80:81], v[56:57]
	v_pk_mul_f32 v[42:43], v[80:81], v[42:43]
	v_pk_mul_f32 v[48:49], v[80:81], v[60:61]
	v_cvt_pk_bf16_f32 v41, v46, v47
	v_cvt_pk_bf16_f32 v46, v42, v43
	v_cvt_pk_bf16_f32 v42, v48, v49
	v_mov_b32_e32 v48, v62
	v_mov_b32_e32 v49, v90
	v_mov_b32_e32 v90, v63
	v_pk_mul_f32 v[48:49], v[80:81], v[48:49]
	v_pk_mul_f32 v[50:51], v[80:81], v[90:91]
	v_cvt_pk_bf16_f32 v47, v48, v49
	v_cvt_pk_bf16_f32 v43, v50, v51
	s_waitcnt lgkmcnt(0)
	s_barrier
	s_waitcnt lgkmcnt(0)
	ds_read_b128 v[196:199], v97
	v_add_u32_e32 v52, v98, v100
	s_add_i32 s50, s50, -1
	s_add_i32 s54, s54, 1
	s_cmp_lg_u32 s50, -2
	s_waitcnt lgkmcnt(0)
	v_pk_mul_f32 v[48:49], v[4:5], v[196:197]
	v_pk_mul_f32 v[50:51], v[6:7], v[198:199]
	v_cvt_pk_bf16_f32 v48, v48, v49
	v_cvt_pk_bf16_f32 v49, v50, v51
	ds_write_b64 v52, v[48:49] offset:45056
	ds_read_b128 v[200:203], v97 offset:64
	s_waitcnt lgkmcnt(0)
	v_pk_mul_f32 v[48:49], v[0:1], v[200:201]
	v_pk_mul_f32 v[50:51], v[2:3], v[202:203]
	v_cvt_pk_bf16_f32 v48, v48, v49
	v_cvt_pk_bf16_f32 v49, v50, v51
	ds_write_b64 v123, v[48:49] offset:45056
	ds_read_b128 v[204:207], v97 offset:128
	s_waitcnt lgkmcnt(0)
	v_pk_mul_f32 v[48:49], v[8:9], v[204:205]
	v_pk_mul_f32 v[50:51], v[10:11], v[206:207]
	v_cvt_pk_bf16_f32 v48, v48, v49
	v_cvt_pk_bf16_f32 v49, v50, v51
	ds_write_b64 v124, v[48:49] offset:45056
	ds_read_b128 v[208:211], v97 offset:192
	s_waitcnt lgkmcnt(0)
	v_pk_mul_f32 v[48:49], v[12:13], v[208:209]
	v_pk_mul_f32 v[50:51], v[14:15], v[210:211]
	v_cvt_pk_bf16_f32 v48, v48, v49
	v_cvt_pk_bf16_f32 v49, v50, v51
	ds_write_b64 v125, v[48:49] offset:45056
	ds_read_b128 v[212:215], v97 offset:256
	s_waitcnt lgkmcnt(0)
	v_pk_mul_f32 v[48:49], v[16:17], v[212:213]
	v_pk_mul_f32 v[50:51], v[18:19], v[214:215]
	v_cvt_pk_bf16_f32 v48, v48, v49
	v_cvt_pk_bf16_f32 v49, v50, v51
	ds_write_b64 v52, v[48:49] offset:45184
	ds_read_b128 v[216:219], v97 offset:320
	s_waitcnt lgkmcnt(0)
	v_pk_mul_f32 v[48:49], v[20:21], v[216:217]
	v_pk_mul_f32 v[50:51], v[22:23], v[218:219]
	v_cvt_pk_bf16_f32 v48, v48, v49
	v_cvt_pk_bf16_f32 v49, v50, v51
	ds_write_b64 v52, v[48:49] offset:45216
	ds_read_b128 v[220:223], v97 offset:384
	s_waitcnt lgkmcnt(0)
	v_pk_mul_f32 v[48:49], v[24:25], v[220:221]
	v_pk_mul_f32 v[50:51], v[26:27], v[222:223]
	v_cvt_pk_bf16_f32 v48, v48, v49
	v_cvt_pk_bf16_f32 v49, v50, v51
	ds_write_b64 v52, v[48:49] offset:45248
	ds_read_b128 v[224:227], v97 offset:448
	s_waitcnt lgkmcnt(0)
	v_pk_mul_f32 v[48:49], v[28:29], v[224:225]
	v_pk_mul_f32 v[50:51], v[30:31], v[226:227]
	v_cvt_pk_bf16_f32 v48, v48, v49
	v_cvt_pk_bf16_f32 v49, v50, v51
	ds_write_b64 v52, v[48:49] offset:45280
	ds_read_b128 v[228:231], v126 offset:17408
	ds_read_b128 v[232:235], v126 offset:17472
	ds_read_b128 v[236:239], v126 offset:17536
	ds_read_b128 v[244:247], v126 offset:17600
	ds_read_b128 v[248:251], v126 offset:21824
	ds_read_b128 v[252:255], v126 offset:21760
	ds_read_b128 v[196:199], v126 offset:21888
	ds_read_b128 v[200:203], v126 offset:21952
	v_add_u32_e32 v48, v98, v96
	ds_read_b128 v[60:63], v48
	ds_read_b128 v[52:55], v48 offset:64
	ds_read_b128 v[56:59], v48 offset:128
	ds_read_b128 v[48:51], v48 offset:192
	s_waitcnt lgkmcnt(3)
	v_mfma_f32_16x16x32_bf16 v[172:175], v[228:231], v[60:63], 0
	ds_read_b128 v[204:207], v126 offset:26176
	s_waitcnt lgkmcnt(3)
	v_mfma_f32_16x16x32_bf16 v[172:175], v[232:235], v[52:55], v[172:175]
	ds_read_b128 v[208:211], v126 offset:26112
	s_waitcnt lgkmcnt(3)
	v_mfma_f32_16x16x32_bf16 v[172:175], v[236:239], v[56:59], v[172:175]
	ds_read_b128 v[212:215], v126 offset:26240
	s_waitcnt lgkmcnt(3)
	v_mfma_f32_16x16x32_bf16 v[172:175], v[244:247], v[48:51], v[172:175]
	ds_read_b128 v[216:219], v126 offset:26304
	s_nop 6
	v_cndmask_b32_e64 v64, v172, 0, s[2:3]
	v_cndmask_b32_e64 v77, v173, 0, s[4:5]
	v_cndmask_b32_e64 v89, v174, 0, s[6:7]
	v_cndmask_b32_e64 v91, v175, 0, s[8:9]
	v_mfma_f32_16x16x32_bf16 v[172:175], v[252:255], v[60:63], 0
	ds_read_b128 v[220:223], v126 offset:30528
	v_cvt_pk_bf16_f32 v90, v64, v77
	v_cvt_pk_bf16_f32 v91, v89, v91
	v_mfma_f32_16x16x32_bf16 v[172:175], v[248:251], v[52:55], v[172:175]
	ds_read_b128 v[224:227], v126 offset:30464
	v_mfma_f32_16x16x32_bf16 v[172:175], v[196:199], v[56:59], v[172:175]
	ds_read_b128 v[228:231], v126 offset:30592
	v_mfma_f32_16x16x32_bf16 v[172:175], v[200:203], v[48:51], v[172:175]
	s_nop 6
	s_nop 0
	v_cndmask_b32_e64 v64, v172, 0, s[10:11]
	v_cndmask_b32_e64 v89, v174, 0, s[14:15]
	v_cndmask_b32_e64 v172, v175, 0, s[16:17]
	v_cndmask_b32_e64 v77, v173, 0, s[12:13]
	v_cvt_pk_bf16_f32 v177, v89, v172
	s_waitcnt lgkmcnt(5)
	v_mfma_f32_16x16x32_bf16 v[172:175], v[208:211], v[60:63], 0
	v_cvt_pk_bf16_f32 v176, v64, v77
	v_mfma_f32_16x16x32_bf16 v[172:175], v[204:207], v[52:55], v[172:175]
	s_waitcnt lgkmcnt(4)
	v_mfma_f32_16x16x32_bf16 v[172:175], v[212:215], v[56:59], v[172:175]
	s_waitcnt lgkmcnt(3)
	v_mfma_f32_16x16x32_bf16 v[172:175], v[216:219], v[48:51], v[172:175]
	s_nop 6
	s_nop 0
	v_cndmask_b32_e64 v64, v172, 0, s[18:19]
	v_cndmask_b32_e64 v89, v174, 0, s[22:23]
	v_cndmask_b32_e64 v172, v175, 0, s[24:25]
	v_cndmask_b32_e64 v77, v173, 0, s[20:21]
	v_cvt_pk_bf16_f32 v193, v89, v172
	s_waitcnt lgkmcnt(1)
	v_mfma_f32_16x16x32_bf16 v[172:175], v[224:227], v[60:63], 0
	v_cvt_pk_bf16_f32 v192, v64, v77
	v_mfma_f32_16x16x32_bf16 v[172:175], v[220:223], v[52:55], v[172:175]
	s_waitcnt lgkmcnt(0)
	v_mfma_f32_16x16x32_bf16 v[172:175], v[228:231], v[56:59], v[172:175]
	ds_read_b128 v[188:191], v126 offset:30656
	s_waitcnt lgkmcnt(0)
	s_barrier
	v_mfma_f32_16x16x32_bf16 v[172:175], v[188:191], v[48:51], v[172:175]
	s_nop 7
	v_cndmask_b32_e64 v64, v172, 0, s[26:27]
	v_cndmask_b32_e64 v77, v173, 0, s[28:29]
	v_cvt_pk_bf16_f32 v172, v64, v77
	v_add_u32_e32 v64, v99, v100
	v_cndmask_b32_e64 v89, v174, 0, s[30:31]
	v_cndmask_b32_e64 v173, v175, 0, s[34:35]
	v_add_u32_e32 v64, 0xf000, v64
	v_cvt_pk_bf16_f32 v173, v89, v173
	ds_write2_b64 v64, v[90:91], v[176:177] offset0:128 offset1:132
	ds_write2_b64 v64, v[192:193], v[172:173] offset0:136 offset1:140
	ds_write_b128 v127, v[36:39] offset:17408
	ds_write_b128 v127, v[44:47] offset:17424
	ds_write_b128 v127, v[32:35] offset:17552
	ds_write_b128 v127, v[40:43] offset:17568
	v_ashrrev_i32_e32 v40, 8, v147
	v_cmp_gt_i32_e32 vcc, 32, v40
	v_lshlrev_b32_e32 v40, 1, v40
	v_subrev_u32_e32 v42, 63, v40
	v_or_b32_e32 v40, 1, v40
	v_ashrrev_i32_e32 v41, 31, v40
	v_cndmask_b32_e32 v41, 0, v41, vcc
	v_cndmask_b32_e32 v40, v42, v40, vcc
	v_cndmask_b32_e32 v64, v133, v134, vcc
	v_lshl_add_u64 v[42:43], s[94:95], 0, v[64:65]
	v_lshlrev_b64 v[40:41], 20, v[40:41]
	v_add_u32_e32 v46, v99, v96
	v_lshl_add_u64 v[40:41], v[42:43], 0, v[40:41]
	v_and_b32_e32 v42, 0x7f800, v148
	s_waitcnt lgkmcnt(0)
	s_barrier
	s_waitcnt lgkmcnt(0)
	ds_read_b128 v[196:199], v46 offset:62464
	ds_read_b128 v[200:203], v46 offset:62528
	ds_read_b128 v[204:207], v128 offset:35840
	ds_read_b128 v[208:211], v128 offset:35904
	ds_read_b128 v[212:215], v126 offset:45056
	ds_read_b128 v[216:219], v126 offset:45120
	ds_read_b128 v[220:223], v126 offset:45184
	ds_read_b128 v[224:227], v126 offset:45248
	v_lshlrev_b32_e32 v64, 1, v42
	s_waitcnt lgkmcnt(5)
	v_mfma_f32_16x16x32_bf16 v[42:45], v[204:207], v[196:199], 0
	ds_read_b128 v[228:231], v128 offset:38208
	ds_read_b128 v[232:235], v128 offset:38144
	v_lshl_add_u64 v[40:41], v[40:41], 0, v[64:65]
	v_mov_b32_e32 v89, v65
	v_lshl_add_u64 v[40:41], v[40:41], 0, v[88:89]
	s_waitcnt lgkmcnt(6)
	v_mfma_f32_16x16x32_bf16 v[42:45], v[208:211], v[200:203], v[42:45]
	ds_read_b128 v[236:239], v126 offset:49408
	ds_read_b128 v[244:247], v126 offset:49472
	v_lshl_add_u64 v[40:41], v[78:79], 1, v[40:41]
	v_mov_b32_e32 v77, v65
	s_waitcnt lgkmcnt(7)
	v_mfma_f32_16x16x32_bf16 v[42:45], v[212:215], v[60:63], v[42:45]
	ds_read_b128 v[248:251], v126 offset:49536
	v_lshl_add_u64 v[40:41], v[40:41], 0, v[76:77]
	v_add_u32_e32 v148, 0xfffe0000, v148
	s_waitcnt lgkmcnt(7)
	v_mfma_f32_16x16x32_bf16 v[42:45], v[216:219], v[52:55], v[42:45]
	ds_read_b128 v[252:255], v126 offset:49600
	v_subrev_u32_e32 v147, 64, v147
	s_waitcnt lgkmcnt(7)
	v_mfma_f32_16x16x32_bf16 v[42:45], v[220:223], v[56:59], v[42:45]
	ds_read_b128 v[204:207], v128 offset:40512
	s_waitcnt lgkmcnt(7)
	v_mfma_f32_16x16x32_bf16 v[42:45], v[224:227], v[48:51], v[42:45]
	ds_read_b128 v[208:211], v128 offset:40448
	s_nop 6
	v_cvt_pk_bf16_f32 v42, v42, v43
	v_cvt_pk_bf16_f32 v43, v44, v45
	global_store_dwordx2 v[40:41], v[42:43], off
	s_waitcnt lgkmcnt(6)
	v_mfma_f32_16x16x32_bf16 v[42:45], v[232:235], v[196:199], 0
	ds_read_b128 v[212:215], v126 offset:53760
	v_mfma_f32_16x16x32_bf16 v[42:45], v[228:231], v[200:203], v[42:45]
	ds_read_b128 v[216:219], v126 offset:53824
	s_waitcnt lgkmcnt(7)
	v_mfma_f32_16x16x32_bf16 v[42:45], v[236:239], v[60:63], v[42:45]
	ds_read_b128 v[220:223], v126 offset:53888
	s_waitcnt lgkmcnt(7)
	v_mfma_f32_16x16x32_bf16 v[42:45], v[244:247], v[52:55], v[42:45]
	ds_read_b128 v[224:227], v128 offset:42752
	s_waitcnt lgkmcnt(7)
	v_mfma_f32_16x16x32_bf16 v[42:45], v[248:251], v[56:59], v[42:45]
	ds_read_b128 v[232:235], v126 offset:58112
	s_waitcnt lgkmcnt(7)
	v_mfma_f32_16x16x32_bf16 v[42:45], v[252:255], v[48:51], v[42:45]
	ds_read_b128 v[228:231], v126 offset:58176
	s_nop 6
	v_cvt_pk_bf16_f32 v42, v42, v43
	v_cvt_pk_bf16_f32 v43, v44, v45
	global_store_dwordx2 v[40:41], v[42:43], off offset:32
	s_waitcnt lgkmcnt(6)
	v_mfma_f32_16x16x32_bf16 v[42:45], v[208:211], v[196:199], 0
	ds_read_b128 v[236:239], v126 offset:58240
	v_mfma_f32_16x16x32_bf16 v[42:45], v[204:207], v[200:203], v[42:45]
	ds_read_b128 v[244:247], v126 offset:58304
	s_waitcnt lgkmcnt(7)
	v_mfma_f32_16x16x32_bf16 v[42:45], v[212:215], v[60:63], v[42:45]
	ds_read_b128 v[248:251], v101
	s_waitcnt lgkmcnt(7)
	v_mfma_f32_16x16x32_bf16 v[42:45], v[216:219], v[52:55], v[42:45]
	ds_read_b128 v[252:255], v128 offset:17408
	s_waitcnt lgkmcnt(7)
	v_mfma_f32_16x16x32_bf16 v[42:45], v[220:223], v[56:59], v[42:45]
	ds_read_b128 v[208:211], v128 offset:17472
	ds_read_b128 v[172:175], v126 offset:53952
	s_waitcnt lgkmcnt(0)
	v_mfma_f32_16x16x32_bf16 v[42:45], v[172:175], v[48:51], v[42:45]
	s_nop 7
	v_cvt_pk_bf16_f32 v42, v42, v43
	v_cvt_pk_bf16_f32 v43, v44, v45
	global_store_dwordx2 v[40:41], v[42:43], off offset:64
	v_mfma_f32_16x16x32_bf16 v[36:39], v[224:227], v[196:199], 0
	ds_read_b128 v[204:207], v101 offset:64
	ds_read_b128 v[42:45], v128 offset:42816
	s_waitcnt lgkmcnt(0)
	v_mfma_f32_16x16x32_bf16 v[32:35], v[42:45], v[200:203], v[36:39]
	s_nop 4
	v_mfma_f32_16x16x32_bf16 v[32:35], v[232:235], v[60:63], v[32:35]
	ds_read_b128 v[212:215], v128 offset:19712
	v_mfma_f32_16x16x32_bf16 v[32:35], v[228:231], v[52:55], v[32:35]
	ds_read_b128 v[216:219], v128 offset:19776
	v_mfma_f32_16x16x32_bf16 v[32:35], v[236:239], v[56:59], v[32:35]
	ds_read_b128 v[220:223], v101 offset:128
	v_mfma_f32_16x16x32_bf16 v[32:35], v[244:247], v[48:51], v[32:35]
	ds_read_b128 v[196:199], v128 offset:22016
	s_nop 7
	v_cvt_pk_bf16_f32 v32, v32, v33
	v_cvt_pk_bf16_f32 v33, v34, v35
	global_store_dwordx2 v[40:41], v[32:33], off offset:96
	ds_read_b128 v[36:39], v46 offset:35840
	ds_read_b128 v[32:35], v46 offset:35904
	v_pk_mul_f32 v[4:5], v[4:5], v[248:249]
	ds_read_b128 v[224:227], v128 offset:22080
	v_pk_mul_f32 v[6:7], v[6:7], v[250:251]
	s_waitcnt lgkmcnt(2)
	s_nop 0
	v_mfma_f32_16x16x32_bf16 v[4:7], v[252:255], v[36:39], v[4:7]
	ds_read_b128 v[200:203], v101 offset:192
	s_waitcnt lgkmcnt(2)
	v_mfma_f32_16x16x32_bf16 v[4:7], v[208:211], v[32:35], v[4:7]
	ds_read_b128 v[232:235], v128 offset:24320
	v_pk_mul_f32 v[0:1], v[0:1], v[204:205]
	ds_read_b128 v[228:231], v128 offset:24384
	v_pk_mul_f32 v[2:3], v[2:3], v[206:207]
	s_nop 1
	v_mfma_f32_16x16x32_bf16 v[0:3], v[212:215], v[36:39], v[0:3]
	ds_read_b128 v[236:239], v101 offset:256
	v_mfma_f32_16x16x32_bf16 v[0:3], v[216:219], v[32:35], v[0:3]
	ds_read_b128 v[244:247], v128 offset:26624
	v_pk_mul_f32 v[8:9], v[8:9], v[220:221]
	ds_read_b128 v[248:251], v128 offset:26688
	v_pk_mul_f32 v[10:11], v[10:11], v[222:223]
	s_nop 1
	v_mfma_f32_16x16x32_bf16 v[8:11], v[196:199], v[36:39], v[8:11]
	ds_read_b128 v[252:255], v101 offset:320
	s_waitcnt lgkmcnt(7)
	v_mfma_f32_16x16x32_bf16 v[8:11], v[224:227], v[32:35], v[8:11]
	ds_read_b128 v[208:211], v128 offset:28928
	s_waitcnt lgkmcnt(7)
	v_pk_mul_f32 v[12:13], v[12:13], v[200:201]
	ds_read_b128 v[204:207], v128 offset:28992
	v_pk_mul_f32 v[14:15], v[14:15], v[202:203]
	s_waitcnt lgkmcnt(7)
	s_nop 0
	v_mfma_f32_16x16x32_bf16 v[12:15], v[232:235], v[36:39], v[12:15]
	ds_read_b128 v[212:215], v101 offset:384
	s_waitcnt lgkmcnt(7)
	v_mfma_f32_16x16x32_bf16 v[12:15], v[228:231], v[32:35], v[12:15]
	ds_read_b128 v[216:219], v128 offset:31232
	s_waitcnt lgkmcnt(7)
	v_pk_mul_f32 v[16:17], v[16:17], v[236:237]
	ds_read_b128 v[220:223], v128 offset:31296
	v_pk_mul_f32 v[18:19], v[18:19], v[238:239]
	s_waitcnt lgkmcnt(7)
	s_nop 0
	v_mfma_f32_16x16x32_bf16 v[16:19], v[244:247], v[36:39], v[16:19]
	ds_read_b128 v[196:199], v101 offset:448
	s_waitcnt lgkmcnt(7)
	v_mfma_f32_16x16x32_bf16 v[16:19], v[248:251], v[32:35], v[16:19]
	s_waitcnt lgkmcnt(6)
	v_pk_mul_f32 v[20:21], v[20:21], v[252:253]
	v_pk_mul_f32 v[22:23], v[22:23], v[254:255]
	s_waitcnt lgkmcnt(5)
	s_nop 0
	v_mfma_f32_16x16x32_bf16 v[20:23], v[208:211], v[36:39], v[20:23]
	s_waitcnt lgkmcnt(4)
	v_mfma_f32_16x16x32_bf16 v[20:23], v[204:207], v[32:35], v[20:23]
	s_waitcnt lgkmcnt(3)
	v_pk_mul_f32 v[24:25], v[24:25], v[212:213]
	v_pk_mul_f32 v[26:27], v[26:27], v[214:215]
	s_waitcnt lgkmcnt(2)
	s_nop 0
	v_mfma_f32_16x16x32_bf16 v[24:27], v[216:219], v[36:39], v[24:27]
	s_waitcnt lgkmcnt(1)
	v_mfma_f32_16x16x32_bf16 v[24:27], v[220:223], v[32:35], v[24:27]
	s_waitcnt lgkmcnt(0)
	v_pk_mul_f32 v[28:29], v[28:29], v[196:197]
	v_pk_mul_f32 v[30:31], v[30:31], v[198:199]
	ds_read_b128 v[40:43], v128 offset:33536
	s_waitcnt lgkmcnt(0)
	v_mfma_f32_16x16x32_bf16 v[28:31], v[40:43], v[36:39], v[28:31]
	ds_read_b128 v[36:39], v128 offset:33600
	s_waitcnt lgkmcnt(0)
	s_barrier
	v_mfma_f32_16x16x32_bf16 v[28:31], v[36:39], v[32:35], v[28:31]
	s_cbranch_scc0 .LBB0_1040

.LBB0_1058:
	v_mov_b32_e32 v37, v34
	v_mov_b32_e32 v34, v33
	v_mov_b32_e32 v36, v32
	v_pk_mul_f32 v[32:33], v[76:77], v[34:35]
	v_mov_b32_e32 v34, v38
	v_mov_b32_e32 v35, v40
	v_pk_mul_f32 v[36:37], v[76:77], v[36:37]
	v_pk_mul_f32 v[34:35], v[76:77], v[34:35]
	v_cvt_pk_bf16_f32 v36, v36, v37
	v_mov_b32_e32 v40, v39
	v_cvt_pk_bf16_f32 v37, v34, v35
	v_mov_b32_e32 v34, v42
	v_mov_b32_e32 v35, v44
	v_mov_b32_e32 v44, v43
	v_pk_mul_f32 v[38:39], v[76:77], v[40:41]
	v_pk_mul_f32 v[34:35], v[76:77], v[34:35]
	v_pk_mul_f32 v[40:41], v[76:77], v[44:45]
	v_cvt_pk_bf16_f32 v32, v32, v33
	v_cvt_pk_bf16_f32 v33, v38, v39
	v_cvt_pk_bf16_f32 v38, v34, v35
	v_cvt_pk_bf16_f32 v34, v40, v41
	v_mov_b32_e32 v40, v46
	v_mov_b32_e32 v41, v48
	v_pk_mul_f32 v[40:41], v[76:77], v[40:41]
	v_mov_b32_e32 v48, v47
	v_pk_mul_f32 v[42:43], v[76:77], v[48:49]
	v_cvt_pk_bf16_f32 v39, v40, v41
	v_mov_b32_e32 v40, v50
	v_mov_b32_e32 v41, v52
	v_mov_b32_e32 v52, v51
	v_cvt_pk_bf16_f32 v35, v42, v43
	v_pk_mul_f32 v[40:41], v[76:77], v[40:41]
	v_pk_mul_f32 v[42:43], v[76:77], v[52:53]
	v_cvt_pk_bf16_f32 v44, v40, v41
	v_cvt_pk_bf16_f32 v40, v42, v43
	v_mov_b32_e32 v42, v54
	v_mov_b32_e32 v43, v56
	v_pk_mul_f32 v[42:43], v[76:77], v[42:43]
	v_mov_b32_e32 v56, v55
	v_cvt_pk_bf16_f32 v45, v42, v43
	v_mov_b32_e32 v42, v58
	v_mov_b32_e32 v43, v60
	v_mov_b32_e32 v60, v59
	v_pk_mul_f32 v[46:47], v[76:77], v[56:57]
	v_pk_mul_f32 v[42:43], v[76:77], v[42:43]
	v_pk_mul_f32 v[48:49], v[76:77], v[60:61]
	v_cvt_pk_bf16_f32 v41, v46, v47
	v_cvt_pk_bf16_f32 v46, v42, v43
	v_cvt_pk_bf16_f32 v42, v48, v49
	v_mov_b32_e32 v48, v62
	v_mov_b32_e32 v49, v86
	v_mov_b32_e32 v86, v63
	v_pk_mul_f32 v[48:49], v[76:77], v[48:49]
	v_pk_mul_f32 v[50:51], v[76:77], v[86:87]
	v_cvt_pk_bf16_f32 v47, v48, v49
	v_cvt_pk_bf16_f32 v43, v50, v51
	s_waitcnt lgkmcnt(0)
	s_barrier
	s_waitcnt lgkmcnt(0)
	ds_read_b128 v[196:199], v93
	v_add_u32_e32 v52, v94, v96
	v_add_u32_e32 v60, v94, v91
	s_add_i32 s52, s52, 1
	v_lshl_add_u64 v[78:79], v[78:79], 0, s[48:49]
	s_waitcnt lgkmcnt(0)
	v_pk_mul_f32 v[48:49], v[4:5], v[196:197]
	v_pk_mul_f32 v[50:51], v[6:7], v[198:199]
	v_cvt_pk_bf16_f32 v48, v48, v49
	v_cvt_pk_bf16_f32 v49, v50, v51
	ds_write_b64 v52, v[48:49] offset:45056
	ds_read_b128 v[200:203], v93 offset:64
	v_lshl_add_u64 v[80:81], v[80:81], 0, s[48:49]
	v_lshl_add_u64 v[82:83], v[82:83], 0, s[50:51]
	s_cmp_lg_u32 s52, 32
	s_waitcnt lgkmcnt(0)
	v_pk_mul_f32 v[48:49], v[0:1], v[200:201]
	v_pk_mul_f32 v[50:51], v[2:3], v[202:203]
	v_cvt_pk_bf16_f32 v48, v48, v49
	v_cvt_pk_bf16_f32 v49, v50, v51
	ds_write_b64 v118, v[48:49] offset:45056
	ds_read_b128 v[204:207], v93 offset:128
	s_waitcnt lgkmcnt(0)
	v_pk_mul_f32 v[48:49], v[8:9], v[204:205]
	v_pk_mul_f32 v[50:51], v[10:11], v[206:207]
	v_cvt_pk_bf16_f32 v48, v48, v49
	v_cvt_pk_bf16_f32 v49, v50, v51
	ds_write_b64 v119, v[48:49] offset:45056
	ds_read_b128 v[208:211], v93 offset:192
	s_waitcnt lgkmcnt(0)
	v_pk_mul_f32 v[48:49], v[12:13], v[208:209]
	v_pk_mul_f32 v[50:51], v[14:15], v[210:211]
	v_cvt_pk_bf16_f32 v48, v48, v49
	v_cvt_pk_bf16_f32 v49, v50, v51
	ds_write_b64 v120, v[48:49] offset:45056
	ds_read_b128 v[212:215], v93 offset:256
	s_waitcnt lgkmcnt(0)
	v_pk_mul_f32 v[48:49], v[16:17], v[212:213]
	v_pk_mul_f32 v[50:51], v[18:19], v[214:215]
	v_cvt_pk_bf16_f32 v48, v48, v49
	v_cvt_pk_bf16_f32 v49, v50, v51
	ds_write_b64 v52, v[48:49] offset:45184
	ds_read_b128 v[216:219], v93 offset:320
	s_waitcnt lgkmcnt(0)
	v_pk_mul_f32 v[48:49], v[20:21], v[216:217]
	v_pk_mul_f32 v[50:51], v[22:23], v[218:219]
	v_cvt_pk_bf16_f32 v48, v48, v49
	v_cvt_pk_bf16_f32 v49, v50, v51
	ds_write_b64 v52, v[48:49] offset:45216
	ds_read_b128 v[220:223], v93 offset:384
	s_waitcnt lgkmcnt(0)
	v_pk_mul_f32 v[48:49], v[24:25], v[220:221]
	v_pk_mul_f32 v[50:51], v[26:27], v[222:223]
	v_cvt_pk_bf16_f32 v48, v48, v49
	v_cvt_pk_bf16_f32 v49, v50, v51
	ds_write_b64 v52, v[48:49] offset:45248
	ds_read_b128 v[224:227], v93 offset:448
	s_waitcnt lgkmcnt(0)
	v_pk_mul_f32 v[48:49], v[28:29], v[224:225]
	v_pk_mul_f32 v[50:51], v[30:31], v[226:227]
	v_cvt_pk_bf16_f32 v48, v48, v49
	v_cvt_pk_bf16_f32 v49, v50, v51
	ds_write_b64 v52, v[48:49] offset:45280
	ds_read_b128 v[228:231], v121 offset:17408
	ds_read_b128 v[232:235], v121 offset:17472
	ds_read_b128 v[236:239], v121 offset:17536
	ds_read_b128 v[244:247], v121 offset:17600
	ds_read_b128 v[248:251], v121 offset:21824
	ds_read_b128 v[252:255], v121 offset:21760
	ds_read_b128 v[196:199], v121 offset:21888
	ds_read_b128 v[200:203], v121 offset:21952
	ds_read_b128 v[48:51], v60
	ds_read_b128 v[52:55], v60 offset:64
	ds_read_b128 v[56:59], v60 offset:128
	ds_read_b128 v[60:63], v60 offset:192
	s_waitcnt lgkmcnt(3)
	v_mfma_f32_16x16x32_bf16 v[164:167], v[228:231], v[48:51], 0
	ds_read_b128 v[204:207], v121 offset:26176
	s_waitcnt lgkmcnt(3)
	v_mfma_f32_16x16x32_bf16 v[164:167], v[232:235], v[52:55], v[164:167]
	ds_read_b128 v[208:211], v121 offset:26112
	s_waitcnt lgkmcnt(3)
	v_mfma_f32_16x16x32_bf16 v[164:167], v[236:239], v[56:59], v[164:167]
	ds_read_b128 v[212:215], v121 offset:26240
	s_waitcnt lgkmcnt(3)
	v_mfma_f32_16x16x32_bf16 v[164:167], v[244:247], v[60:63], v[164:167]
	ds_read_b128 v[216:219], v121 offset:26304
	s_nop 6
	v_cndmask_b32_e64 v86, v164, 0, s[0:1]
	v_cndmask_b32_e64 v87, 0, v165, s[2:3]
	v_cndmask_b32_e64 v163, v166, 0, s[4:5]
	v_cndmask_b32_e64 v164, v167, 0, s[6:7]
	v_cvt_pk_bf16_f32 v86, v86, v87
	v_cvt_pk_bf16_f32 v87, v163, v164
	v_mfma_f32_16x16x32_bf16 v[164:167], v[252:255], v[48:51], 0
	ds_read_b128 v[220:223], v121 offset:30528
	v_mfma_f32_16x16x32_bf16 v[164:167], v[248:251], v[52:55], v[164:167]
	ds_read_b128 v[224:227], v121 offset:30464
	v_mfma_f32_16x16x32_bf16 v[164:167], v[196:199], v[56:59], v[164:167]
	ds_read_b128 v[228:231], v121 offset:30592
	v_mfma_f32_16x16x32_bf16 v[164:167], v[200:203], v[60:63], v[164:167]
	s_nop 6
	s_nop 0
	v_cndmask_b32_e64 v163, v164, 0, s[8:9]
	v_cndmask_b32_e64 v164, v165, 0, s[10:11]
	v_cndmask_b32_e64 v165, v166, 0, s[12:13]
	v_cndmask_b32_e64 v166, v167, 0, s[14:15]
	v_cvt_pk_bf16_f32 v172, v163, v164
	v_cvt_pk_bf16_f32 v173, v165, v166
	s_waitcnt lgkmcnt(5)
	v_mfma_f32_16x16x32_bf16 v[164:167], v[208:211], v[48:51], 0
	v_mfma_f32_16x16x32_bf16 v[164:167], v[204:207], v[52:55], v[164:167]
	s_waitcnt lgkmcnt(4)
	v_mfma_f32_16x16x32_bf16 v[164:167], v[212:215], v[56:59], v[164:167]
	s_waitcnt lgkmcnt(3)
	v_mfma_f32_16x16x32_bf16 v[164:167], v[216:219], v[60:63], v[164:167]
	s_nop 6
	s_nop 0
	v_cndmask_b32_e64 v163, v164, 0, s[16:17]
	v_cndmask_b32_e64 v164, v165, 0, s[18:19]
	v_cndmask_b32_e64 v165, v166, 0, s[20:21]
	v_cndmask_b32_e64 v166, v167, 0, s[22:23]
	v_cvt_pk_bf16_f32 v174, v163, v164
	v_cvt_pk_bf16_f32 v175, v165, v166
	s_waitcnt lgkmcnt(1)
	v_mfma_f32_16x16x32_bf16 v[164:167], v[224:227], v[48:51], 0
	v_mfma_f32_16x16x32_bf16 v[164:167], v[220:223], v[52:55], v[164:167]
	s_waitcnt lgkmcnt(0)
	v_mfma_f32_16x16x32_bf16 v[164:167], v[228:231], v[56:59], v[164:167]
	ds_read_b128 v[168:171], v121 offset:30656
	s_waitcnt lgkmcnt(0)
	s_barrier
	v_mfma_f32_16x16x32_bf16 v[164:167], v[168:171], v[60:63], v[164:167]
	s_nop 7
	v_cndmask_b32_e64 v163, v164, 0, s[24:25]
	v_cndmask_b32_e64 v164, v165, 0, s[26:27]
	v_cvt_pk_bf16_f32 v164, v163, v164
	v_add_u32_e32 v163, v95, v96
	v_cndmask_b32_e64 v165, v166, 0, s[28:29]
	v_cndmask_b32_e64 v166, v167, 0, s[30:31]
	v_add_u32_e32 v163, 0xf000, v163
	v_cvt_pk_bf16_f32 v165, v165, v166
	ds_write2_b64 v163, v[86:87], v[172:173] offset0:128 offset1:132
	ds_write2_b64 v163, v[174:175], v[164:165] offset0:136 offset1:140
	ds_write_b128 v122, v[36:39] offset:17408
	ds_write_b128 v122, v[44:47] offset:17424
	ds_write_b128 v122, v[32:35] offset:17552
	ds_write_b128 v122, v[40:43] offset:17568
	v_add_u32_e32 v86, v95, v91
	s_waitcnt lgkmcnt(0)
	s_barrier
	s_waitcnt lgkmcnt(0)
	ds_read_b128 v[196:199], v86 offset:62464
	ds_read_b128 v[200:203], v86 offset:62528
	ds_read_b128 v[204:207], v123 offset:35840
	ds_read_b128 v[208:211], v123 offset:35904
	ds_read_b128 v[212:215], v121 offset:45056
	ds_read_b128 v[216:219], v121 offset:45120
	ds_read_b128 v[220:223], v121 offset:45184
	ds_read_b128 v[224:227], v121 offset:45248
	s_waitcnt lgkmcnt(5)
	v_mfma_f32_16x16x32_bf16 v[40:43], v[204:207], v[196:199], 0
	ds_read_b128 v[228:231], v123 offset:38208
	ds_read_b128 v[232:235], v123 offset:38144
	s_waitcnt lgkmcnt(6)
	v_mfma_f32_16x16x32_bf16 v[40:43], v[208:211], v[200:203], v[40:43]
	ds_read_b128 v[236:239], v121 offset:49408
	ds_read_b128 v[244:247], v121 offset:49472
	s_waitcnt lgkmcnt(7)
	v_mfma_f32_16x16x32_bf16 v[40:43], v[212:215], v[48:51], v[40:43]
	ds_read_b128 v[248:251], v121 offset:49536
	s_waitcnt lgkmcnt(7)
	v_mfma_f32_16x16x32_bf16 v[40:43], v[216:219], v[52:55], v[40:43]
	ds_read_b128 v[252:255], v121 offset:49600
	s_waitcnt lgkmcnt(7)
	v_mfma_f32_16x16x32_bf16 v[40:43], v[220:223], v[56:59], v[40:43]
	ds_read_b128 v[204:207], v123 offset:40512
	s_waitcnt lgkmcnt(7)
	v_mfma_f32_16x16x32_bf16 v[40:43], v[224:227], v[60:63], v[40:43]
	ds_read_b128 v[208:211], v123 offset:40448
	s_nop 6
	v_cvt_pk_bf16_f32 v40, v40, v41
	v_cvt_pk_bf16_f32 v41, v42, v43
	global_store_dwordx2 v[84:85], v[40:41], off offset:-64
	s_waitcnt lgkmcnt(6)
	v_mfma_f32_16x16x32_bf16 v[40:43], v[232:235], v[196:199], 0
	ds_read_b128 v[212:215], v121 offset:53760
	v_mfma_f32_16x16x32_bf16 v[40:43], v[228:231], v[200:203], v[40:43]
	ds_read_b128 v[216:219], v121 offset:53824
	s_waitcnt lgkmcnt(7)
	v_mfma_f32_16x16x32_bf16 v[40:43], v[236:239], v[48:51], v[40:43]
	ds_read_b128 v[220:223], v121 offset:53888
	s_waitcnt lgkmcnt(7)
	v_mfma_f32_16x16x32_bf16 v[40:43], v[244:247], v[52:55], v[40:43]
	ds_read_b128 v[224:227], v123 offset:42752
	s_waitcnt lgkmcnt(7)
	v_mfma_f32_16x16x32_bf16 v[40:43], v[248:251], v[56:59], v[40:43]
	ds_read_b128 v[232:235], v123 offset:42816
	s_waitcnt lgkmcnt(7)
	v_mfma_f32_16x16x32_bf16 v[40:43], v[252:255], v[60:63], v[40:43]
	ds_read_b128 v[228:231], v121 offset:58112
	s_nop 6
	v_cvt_pk_bf16_f32 v40, v40, v41
	v_cvt_pk_bf16_f32 v41, v42, v43
	global_store_dwordx2 v[84:85], v[40:41], off offset:-32
	s_waitcnt lgkmcnt(6)
	v_mfma_f32_16x16x32_bf16 v[40:43], v[208:211], v[196:199], 0
	ds_read_b128 v[236:239], v121 offset:58176
	v_mfma_f32_16x16x32_bf16 v[40:43], v[204:207], v[200:203], v[40:43]
	ds_read_b128 v[244:247], v121 offset:58240
	s_waitcnt lgkmcnt(7)
	v_mfma_f32_16x16x32_bf16 v[40:43], v[212:215], v[48:51], v[40:43]
	ds_read_b128 v[248:251], v121 offset:58304
	s_waitcnt lgkmcnt(7)
	v_mfma_f32_16x16x32_bf16 v[40:43], v[216:219], v[52:55], v[40:43]
	ds_read_b128 v[252:255], v97
	s_waitcnt lgkmcnt(7)
	v_mfma_f32_16x16x32_bf16 v[40:43], v[220:223], v[56:59], v[40:43]
	ds_read_b128 v[208:211], v123 offset:17408
	ds_read_b128 v[44:47], v121 offset:53952
	s_waitcnt lgkmcnt(0)
	v_mfma_f32_16x16x32_bf16 v[40:43], v[44:47], v[60:63], v[40:43]
	s_nop 7
	v_cvt_pk_bf16_f32 v40, v40, v41
	v_cvt_pk_bf16_f32 v41, v42, v43
	global_store_dwordx2 v[84:85], v[40:41], off
	v_mfma_f32_16x16x32_bf16 v[32:35], v[224:227], v[196:199], 0
	ds_read_b128 v[204:207], v123 offset:17472
	v_mfma_f32_16x16x32_bf16 v[32:35], v[232:235], v[200:203], v[32:35]
	ds_read_b128 v[212:215], v97 offset:64
	v_mfma_f32_16x16x32_bf16 v[32:35], v[228:231], v[48:51], v[32:35]
	ds_read_b128 v[216:219], v123 offset:19712
	v_mfma_f32_16x16x32_bf16 v[32:35], v[236:239], v[52:55], v[32:35]
	ds_read_b128 v[220:223], v123 offset:19776
	v_mfma_f32_16x16x32_bf16 v[32:35], v[244:247], v[56:59], v[32:35]
	ds_read_b128 v[196:199], v97 offset:128
	v_mfma_f32_16x16x32_bf16 v[32:35], v[248:251], v[60:63], v[32:35]
	ds_read_b128 v[224:227], v123 offset:22016
	s_nop 7
	v_cvt_pk_bf16_f32 v32, v32, v33
	v_cvt_pk_bf16_f32 v33, v34, v35
	global_store_dwordx2 v[84:85], v[32:33], off offset:32
	ds_read_b128 v[36:39], v86 offset:35840
	ds_read_b128 v[32:35], v86 offset:35904
	v_lshl_add_u64 v[84:85], v[84:85], 0, s[50:51]
	v_pk_mul_f32 v[4:5], v[4:5], v[252:253]
	ds_read_b128 v[200:203], v123 offset:22080
	v_pk_mul_f32 v[6:7], v[6:7], v[254:255]
	s_waitcnt lgkmcnt(2)
	s_nop 0
	v_mfma_f32_16x16x32_bf16 v[4:7], v[208:211], v[36:39], v[4:7]
	ds_read_b128 v[232:235], v97 offset:192
	s_waitcnt lgkmcnt(2)
	v_mfma_f32_16x16x32_bf16 v[4:7], v[204:207], v[32:35], v[4:7]
	ds_read_b128 v[228:231], v123 offset:24320
	v_pk_mul_f32 v[0:1], v[0:1], v[212:213]
	ds_read_b128 v[236:239], v123 offset:24384
	v_pk_mul_f32 v[2:3], v[2:3], v[214:215]
	s_nop 1
	v_mfma_f32_16x16x32_bf16 v[0:3], v[216:219], v[36:39], v[0:3]
	ds_read_b128 v[244:247], v97 offset:256
	v_mfma_f32_16x16x32_bf16 v[0:3], v[220:223], v[32:35], v[0:3]
	ds_read_b128 v[248:251], v123 offset:26624
	v_pk_mul_f32 v[8:9], v[8:9], v[196:197]
	ds_read_b128 v[252:255], v123 offset:26688
	v_pk_mul_f32 v[10:11], v[10:11], v[198:199]
	s_nop 1
	v_mfma_f32_16x16x32_bf16 v[8:11], v[224:227], v[36:39], v[8:11]
	ds_read_b128 v[208:211], v97 offset:320
	s_waitcnt lgkmcnt(7)
	v_mfma_f32_16x16x32_bf16 v[8:11], v[200:203], v[32:35], v[8:11]
	ds_read_b128 v[204:207], v123 offset:28928
	s_waitcnt lgkmcnt(7)
	v_pk_mul_f32 v[12:13], v[12:13], v[232:233]
	ds_read_b128 v[212:215], v123 offset:28992
	v_pk_mul_f32 v[14:15], v[14:15], v[234:235]
	s_waitcnt lgkmcnt(7)
	s_nop 0
	v_mfma_f32_16x16x32_bf16 v[12:15], v[228:231], v[36:39], v[12:15]
	ds_read_b128 v[216:219], v97 offset:384
	s_waitcnt lgkmcnt(7)
	v_mfma_f32_16x16x32_bf16 v[12:15], v[236:239], v[32:35], v[12:15]
	ds_read_b128 v[220:223], v123 offset:31232
	s_waitcnt lgkmcnt(7)
	v_pk_mul_f32 v[16:17], v[16:17], v[244:245]
	ds_read_b128 v[196:199], v123 offset:31296
	v_pk_mul_f32 v[18:19], v[18:19], v[246:247]
	s_waitcnt lgkmcnt(7)
	s_nop 0
	v_mfma_f32_16x16x32_bf16 v[16:19], v[248:251], v[36:39], v[16:19]
	ds_read_b128 v[224:227], v97 offset:448
	s_waitcnt lgkmcnt(7)
	v_mfma_f32_16x16x32_bf16 v[16:19], v[252:255], v[32:35], v[16:19]
	s_waitcnt lgkmcnt(6)
	v_pk_mul_f32 v[20:21], v[20:21], v[208:209]
	v_pk_mul_f32 v[22:23], v[22:23], v[210:211]
	s_waitcnt lgkmcnt(5)
	s_nop 0
	v_mfma_f32_16x16x32_bf16 v[20:23], v[204:207], v[36:39], v[20:23]
	s_waitcnt lgkmcnt(4)
	v_mfma_f32_16x16x32_bf16 v[20:23], v[212:215], v[32:35], v[20:23]
	s_waitcnt lgkmcnt(3)
	v_pk_mul_f32 v[24:25], v[24:25], v[216:217]
	v_pk_mul_f32 v[26:27], v[26:27], v[218:219]
	s_waitcnt lgkmcnt(2)
	s_nop 0
	v_mfma_f32_16x16x32_bf16 v[24:27], v[220:223], v[36:39], v[24:27]
	s_waitcnt lgkmcnt(1)
	v_mfma_f32_16x16x32_bf16 v[24:27], v[196:199], v[32:35], v[24:27]
	s_waitcnt lgkmcnt(0)
	v_pk_mul_f32 v[28:29], v[28:29], v[224:225]
	v_pk_mul_f32 v[30:31], v[30:31], v[226:227]
	ds_read_b128 v[40:43], v123 offset:33536
	s_waitcnt lgkmcnt(0)
	v_mfma_f32_16x16x32_bf16 v[28:31], v[40:43], v[36:39], v[28:31]
	ds_read_b128 v[36:39], v123 offset:33600
	s_waitcnt lgkmcnt(0)
	s_barrier
	v_mfma_f32_16x16x32_bf16 v[28:31], v[36:39], v[32:35], v[28:31]
	s_cbranch_scc0 .LBB0_1052

.LBB0_1461:
	s_or_b64 exec, exec, s[58:59]
	v_sub_f32_e32 v32, v66, v33
	v_exp_f32_e32 v66, v32
	v_sub_f32_e32 v32, v75, v35
	v_exp_f32_e32 v160, v32
	v_mov_b32_e32 v32, v38
	v_mov_b32_e32 v33, v36
	v_pk_mul_f32 v[32:33], v[66:67], v[32:33] op_sel_hi:[0,1]
	v_mov_b32_e32 v36, v39
	v_cvt_pk_bf16_f32 v39, v32, v33
	v_mov_b32_e32 v32, v42
	v_mov_b32_e32 v33, v40
	v_pk_mul_f32 v[32:33], v[66:67], v[32:33] op_sel_hi:[0,1]
	v_mov_b32_e32 v40, v43
	v_cvt_pk_bf16_f32 v38, v32, v33
	v_mov_b32_e32 v32, v46
	v_mov_b32_e32 v33, v44
	v_mov_b32_e32 v44, v47
	v_pk_mul_f32 v[34:35], v[160:161], v[36:37] op_sel_hi:[0,1]
	v_pk_mul_f32 v[36:37], v[160:161], v[40:41] op_sel_hi:[0,1]
	v_pk_mul_f32 v[32:33], v[66:67], v[32:33] op_sel_hi:[0,1]
	v_pk_mul_f32 v[40:41], v[160:161], v[44:45] op_sel_hi:[0,1]
	v_cvt_pk_bf16_f32 v35, v34, v35
	v_cvt_pk_bf16_f32 v34, v36, v37
	v_cvt_pk_bf16_f32 v37, v32, v33
	v_cvt_pk_bf16_f32 v33, v40, v41
	v_mov_b32_e32 v40, v50
	v_mov_b32_e32 v41, v48
	v_pk_mul_f32 v[40:41], v[66:67], v[40:41] op_sel_hi:[0,1]
	v_cvt_pk_bf16_f32 v36, v40, v41
	v_mov_b32_e32 v40, v56
	v_mov_b32_e32 v41, v52
	v_pk_mul_f32 v[40:41], v[66:67], v[40:41] op_sel_hi:[0,1]
	v_mov_b32_e32 v48, v51
	v_cvt_pk_bf16_f32 v51, v40, v41
	v_mov_b32_e32 v40, v96
	v_mov_b32_e32 v41, v60
	v_pk_mul_f32 v[42:43], v[160:161], v[48:49] op_sel_hi:[0,1]
	v_mov_b32_e32 v52, v57
	v_pk_mul_f32 v[40:41], v[66:67], v[40:41] op_sel_hi:[0,1]
	v_mov_b32_e32 v60, v97
	v_cvt_pk_bf16_f32 v32, v42, v43
	v_pk_mul_f32 v[42:43], v[160:161], v[52:53] op_sel_hi:[0,1]
	v_pk_mul_f32 v[44:45], v[160:161], v[60:61] op_sel_hi:[0,1]
	v_cvt_pk_bf16_f32 v50, v40, v41
	v_mov_b32_e32 v40, v62
	v_mov_b32_e32 v41, v98
	v_mov_b32_e32 v98, v63
	v_cvt_pk_bf16_f32 v43, v42, v43
	v_cvt_pk_bf16_f32 v42, v44, v45
	v_pk_mul_f32 v[40:41], v[66:67], v[40:41] op_sel_hi:[0,1]
	v_pk_mul_f32 v[44:45], v[160:161], v[98:99] op_sel_hi:[0,1]
	v_cvt_pk_bf16_f32 v49, v40, v41
	v_cvt_pk_bf16_f32 v41, v44, v45
	v_mov_b32_e32 v44, v54
	v_mov_b32_e32 v45, v58
	v_mov_b32_e32 v58, v55
	v_pk_mul_f32 v[44:45], v[66:67], v[44:45] op_sel_hi:[0,1]
	v_pk_mul_f32 v[46:47], v[160:161], v[58:59] op_sel_hi:[0,1]
	v_cvt_pk_bf16_f32 v48, v44, v45
	v_cvt_pk_bf16_f32 v40, v46, v47
	s_waitcnt lgkmcnt(0)
	s_barrier
	s_waitcnt lgkmcnt(0)
	ds_read_b128 v[216:219], v108
	v_add_u32_e32 v52, v109, v111
	v_add_u32_e32 v92, -1, v92
	s_add_i32 s73, s73, 1
	s_waitcnt lgkmcnt(0)
	v_pk_mul_f32 v[44:45], v[16:17], v[216:217]
	v_pk_mul_f32 v[46:47], v[18:19], v[218:219]
	v_cvt_pk_bf16_f32 v44, v44, v45
	v_cvt_pk_bf16_f32 v45, v46, v47
	ds_write_b64 v52, v[44:45] offset:45056
	ds_read_b128 v[220:223], v108 offset:64
	s_waitcnt lgkmcnt(0)
	v_pk_mul_f32 v[44:45], v[0:1], v[220:221]
	v_pk_mul_f32 v[46:47], v[2:3], v[222:223]
	v_cvt_pk_bf16_f32 v44, v44, v45
	v_cvt_pk_bf16_f32 v45, v46, v47
	ds_write_b64 v116, v[44:45] offset:45056
	ds_read_b128 v[224:227], v108 offset:128
	s_waitcnt lgkmcnt(0)
	v_pk_mul_f32 v[44:45], v[8:9], v[224:225]
	v_pk_mul_f32 v[46:47], v[10:11], v[226:227]
	v_cvt_pk_bf16_f32 v44, v44, v45
	v_cvt_pk_bf16_f32 v45, v46, v47
	ds_write_b64 v117, v[44:45] offset:45056
	ds_read_b128 v[228:231], v108 offset:192
	s_waitcnt lgkmcnt(0)
	v_pk_mul_f32 v[44:45], v[4:5], v[228:229]
	v_pk_mul_f32 v[46:47], v[6:7], v[230:231]
	v_cvt_pk_bf16_f32 v44, v44, v45
	v_cvt_pk_bf16_f32 v45, v46, v47
	ds_write_b64 v118, v[44:45] offset:45056
	ds_read_b128 v[232:235], v108 offset:256
	s_waitcnt lgkmcnt(0)
	v_pk_mul_f32 v[44:45], v[20:21], v[232:233]
	v_pk_mul_f32 v[46:47], v[22:23], v[234:235]
	v_cvt_pk_bf16_f32 v44, v44, v45
	v_cvt_pk_bf16_f32 v45, v46, v47
	ds_write_b64 v52, v[44:45] offset:45184
	ds_read_b128 v[236:239], v108 offset:320
	s_waitcnt lgkmcnt(0)
	v_pk_mul_f32 v[44:45], v[12:13], v[236:237]
	v_pk_mul_f32 v[46:47], v[14:15], v[238:239]
	v_cvt_pk_bf16_f32 v44, v44, v45
	v_cvt_pk_bf16_f32 v45, v46, v47
	ds_write_b64 v52, v[44:45] offset:45216
	ds_read_b128 v[244:247], v108 offset:384
	s_waitcnt lgkmcnt(0)
	v_pk_mul_f32 v[44:45], v[24:25], v[244:245]
	v_pk_mul_f32 v[46:47], v[26:27], v[246:247]
	v_cvt_pk_bf16_f32 v44, v44, v45
	v_cvt_pk_bf16_f32 v45, v46, v47
	ds_write_b64 v52, v[44:45] offset:45248
	ds_read_b128 v[248:251], v108 offset:448
	s_waitcnt lgkmcnt(0)
	v_pk_mul_f32 v[44:45], v[28:29], v[248:249]
	v_pk_mul_f32 v[46:47], v[30:31], v[250:251]
	v_cvt_pk_bf16_f32 v44, v44, v45
	v_cvt_pk_bf16_f32 v45, v46, v47
	ds_write_b64 v52, v[44:45] offset:45280
	ds_read_b128 v[252:255], v119 offset:17408
	ds_read_b128 v[216:219], v119 offset:17472
	ds_read_b128 v[220:223], v119 offset:21824
	ds_read_b128 v[224:227], v119 offset:17536
	ds_read_b128 v[228:231], v119 offset:17600
	ds_read_b128 v[232:235], v119 offset:21760
	ds_read_b128 v[236:239], v119 offset:21888
	ds_read_b128 v[244:247], v119 offset:21952
	v_add_u32_e32 v44, v109, v107
	ds_read_b128 v[60:63], v44
	ds_read_b128 v[52:55], v44 offset:64
	ds_read_b128 v[56:59], v44 offset:128
	ds_read_b128 v[44:47], v44 offset:192
	s_waitcnt lgkmcnt(3)
	v_mfma_f32_16x16x32_bf16 v[96:99], v[252:255], v[60:63], 0
	ds_read_b128 v[248:251], v119 offset:26176
	s_waitcnt lgkmcnt(3)
	v_mfma_f32_16x16x32_bf16 v[96:99], v[216:219], v[52:55], v[96:99]
	ds_read_b128 v[252:255], v119 offset:26112
	s_waitcnt lgkmcnt(3)
	v_mfma_f32_16x16x32_bf16 v[96:99], v[224:227], v[56:59], v[96:99]
	ds_read_b128 v[216:219], v119 offset:26240
	s_waitcnt lgkmcnt(3)
	v_mfma_f32_16x16x32_bf16 v[96:99], v[228:231], v[44:47], v[96:99]
	ds_read_b128 v[224:227], v119 offset:26304
	s_nop 6
	v_cndmask_b32_e64 v66, v96, 0, s[8:9]
	v_mfma_f32_16x16x32_bf16 v[160:163], v[232:235], v[60:63], 0
	ds_read_b128 v[228:231], v119 offset:30528
	v_cndmask_b32_e64 v75, v97, 0, s[10:11]
	v_cndmask_b32_e64 v95, v98, 0, s[12:13]
	v_cndmask_b32_e64 v97, v99, 0, s[14:15]
	v_mfma_f32_16x16x32_bf16 v[160:163], v[220:223], v[52:55], v[160:163]
	ds_read_b128 v[232:235], v119 offset:30464
	v_cvt_pk_bf16_f32 v96, v66, v75
	v_cvt_pk_bf16_f32 v97, v95, v97
	v_mfma_f32_16x16x32_bf16 v[160:163], v[236:239], v[56:59], v[160:163]
	ds_read_b128 v[220:223], v119 offset:30592
	v_mfma_f32_16x16x32_bf16 v[160:163], v[244:247], v[44:47], v[160:163]
	s_nop 6
	s_nop 0
	v_cndmask_b32_e64 v66, v160, 0, s[16:17]
	v_cndmask_b32_e64 v75, v161, 0, s[18:19]
	v_cndmask_b32_e64 v95, v162, 0, s[20:21]
	v_cndmask_b32_e64 v99, v163, 0, s[22:23]
	s_waitcnt lgkmcnt(5)
	v_mfma_f32_16x16x32_bf16 v[160:163], v[252:255], v[60:63], 0
	v_cvt_pk_bf16_f32 v98, v66, v75
	v_cvt_pk_bf16_f32 v99, v95, v99
	v_mfma_f32_16x16x32_bf16 v[160:163], v[248:251], v[52:55], v[160:163]
	s_waitcnt lgkmcnt(4)
	v_mfma_f32_16x16x32_bf16 v[160:163], v[216:219], v[56:59], v[160:163]
	s_waitcnt lgkmcnt(3)
	v_mfma_f32_16x16x32_bf16 v[160:163], v[224:227], v[44:47], v[160:163]
	s_nop 6
	s_nop 0
	v_cndmask_b32_e64 v66, v160, 0, s[24:25]
	v_cndmask_b32_e64 v95, v162, 0, s[28:29]
	v_cndmask_b32_e64 v160, v163, 0, s[30:31]
	v_cndmask_b32_e64 v75, v161, 0, s[26:27]
	v_cvt_pk_bf16_f32 v169, v95, v160
	s_waitcnt lgkmcnt(1)
	v_mfma_f32_16x16x32_bf16 v[160:163], v[232:235], v[60:63], 0
	v_cvt_pk_bf16_f32 v168, v66, v75
	v_mfma_f32_16x16x32_bf16 v[160:163], v[228:231], v[52:55], v[160:163]
	s_waitcnt lgkmcnt(0)
	v_mfma_f32_16x16x32_bf16 v[160:163], v[220:223], v[56:59], v[160:163]
	ds_read_b128 v[164:167], v119 offset:30656
	s_waitcnt lgkmcnt(0)
	s_barrier
	v_mfma_f32_16x16x32_bf16 v[160:163], v[164:167], v[44:47], v[160:163]
	s_nop 7
	v_cndmask_b32_e64 v66, v160, 0, s[34:35]
	v_cndmask_b32_e64 v75, v161, 0, s[36:37]
	v_cvt_pk_bf16_f32 v160, v66, v75
	v_add_u32_e32 v66, v110, v111
	v_cndmask_b32_e64 v95, v162, 0, s[38:39]
	v_cndmask_b32_e64 v161, v163, 0, s[40:41]
	v_add_u32_e32 v66, 0xf000, v66
	v_cvt_pk_bf16_f32 v161, v95, v161
	ds_write2_b64 v66, v[96:97], v[98:99] offset0:128 offset1:132
	ds_write2_b64 v66, v[168:169], v[160:161] offset0:136 offset1:140
	ds_write_b128 v120, v[48:51] offset:17408
	ds_write_b128 v120, v[36:39] offset:17424
	ds_write_b128 v120, v[40:43] offset:17552
	ds_write_b128 v120, v[32:35] offset:17568
	v_add_u32_e32 v160, v110, v107
	s_waitcnt lgkmcnt(0)
	s_barrier
	s_waitcnt lgkmcnt(0)
	ds_read_b128 v[216:219], v160 offset:62464
	ds_read_b128 v[220:223], v160 offset:62528
	ds_read_b128 v[224:227], v121 offset:35840
	ds_read_b128 v[228:231], v121 offset:35904
	ds_read_b128 v[232:235], v119 offset:45056
	ds_read_b128 v[236:239], v119 offset:45120
	ds_read_b128 v[244:247], v119 offset:45184
	ds_read_b128 v[248:251], v119 offset:45248
	s_waitcnt lgkmcnt(5)
	v_mfma_f32_16x16x32_bf16 v[48:51], v[224:227], v[216:219], 0
	ds_read_b128 v[252:255], v121 offset:38144
	ds_read_b128 v[224:227], v121 offset:38208
	v_ashrrev_i32_e32 v40, 9, v71
	v_cmp_gt_i32_e32 vcc, 32, v40
	v_lshlrev_b32_e32 v40, 1, v40
	s_waitcnt lgkmcnt(6)
	v_mfma_f32_16x16x32_bf16 v[48:51], v[228:231], v[220:223], v[48:51]
	ds_read_b128 v[228:231], v119 offset:49408
	v_subrev_u32_e32 v42, 63, v40
	v_or_b32_e32 v40, 1, v40
	s_waitcnt lgkmcnt(6)
	v_mfma_f32_16x16x32_bf16 v[48:51], v[232:235], v[60:63], v[48:51]
	ds_read_b128 v[232:235], v119 offset:49472
	v_ashrrev_i32_e32 v41, 31, v40
	v_cndmask_b32_e32 v41, 0, v41, vcc
	s_waitcnt lgkmcnt(6)
	v_mfma_f32_16x16x32_bf16 v[48:51], v[236:239], v[52:55], v[48:51]
	ds_read_b128 v[236:239], v119 offset:49536
	v_cndmask_b32_e32 v40, v42, v40, vcc
	v_cndmask_b32_e32 v66, v122, v123, vcc
	s_waitcnt lgkmcnt(6)
	v_mfma_f32_16x16x32_bf16 v[48:51], v[244:247], v[56:59], v[48:51]
	ds_read_b128 v[244:247], v119 offset:49600
	v_lshl_add_u64 v[42:43], s[94:95], 0, v[66:67]
	v_lshlrev_b64 v[40:41], 20, v[40:41]
	s_waitcnt lgkmcnt(6)
	v_mfma_f32_16x16x32_bf16 v[48:51], v[248:251], v[44:47], v[48:51]
	ds_read_b128 v[248:251], v121 offset:40512
	v_lshl_add_u64 v[40:41], v[42:43], 0, v[40:41]
	v_and_b32_e32 v42, 0x7fc00, v73
	v_lshlrev_b32_e32 v66, 1, v42
	s_nop 4
	v_cvt_pk_bf16_f32 v42, v48, v49
	v_cvt_pk_bf16_f32 v43, v50, v51
	s_waitcnt lgkmcnt(6)
	v_mfma_f32_16x16x32_bf16 v[48:51], v[252:255], v[216:219], 0
	ds_read_b128 v[252:255], v121 offset:40448
	v_lshl_add_u64 v[40:41], v[40:41], 0, v[66:67]
	v_mov_b32_e32 v95, v67
	v_lshl_add_u64 v[40:41], v[40:41], 0, v[94:95]
	s_waitcnt lgkmcnt(6)
	v_mfma_f32_16x16x32_bf16 v[48:51], v[224:227], v[220:223], v[48:51]
	ds_read_b128 v[224:227], v119 offset:53760
	v_lshl_add_u64 v[40:41], v[80:81], 1, v[40:41]
	v_mov_b32_e32 v75, v67
	s_waitcnt lgkmcnt(6)
	v_mfma_f32_16x16x32_bf16 v[48:51], v[228:231], v[60:63], v[48:51]
	ds_read_b128 v[228:231], v119 offset:53824
	v_lshl_add_u64 v[40:41], v[40:41], 0, v[74:75]
	global_store_dwordx2 v[40:41], v[42:43], off
	s_waitcnt lgkmcnt(6)
	v_mfma_f32_16x16x32_bf16 v[48:51], v[232:235], v[52:55], v[48:51]
	ds_read_b128 v[232:235], v119 offset:53888
	v_cmp_eq_u32_e32 vcc, -2, v92
	v_add_u32_e32 v73, 0xffff0000, v73
	s_waitcnt lgkmcnt(6)
	v_mfma_f32_16x16x32_bf16 v[48:51], v[236:239], v[56:59], v[48:51]
	ds_read_b128 v[236:239], v121 offset:42752
	v_subrev_u32_e32 v71, 64, v71
	s_or_b64 s[56:57], vcc, s[56:57]
	s_waitcnt lgkmcnt(6)
	v_mfma_f32_16x16x32_bf16 v[48:51], v[244:247], v[44:47], v[48:51]
	ds_read_b128 v[244:247], v119 offset:58112
	s_nop 6
	v_cvt_pk_bf16_f32 v42, v48, v49
	v_cvt_pk_bf16_f32 v43, v50, v51
	s_waitcnt lgkmcnt(5)
	v_mfma_f32_16x16x32_bf16 v[48:51], v[252:255], v[216:219], 0
	ds_read_b128 v[252:255], v119 offset:58176
	global_store_dwordx2 v[40:41], v[42:43], off offset:32
	v_mfma_f32_16x16x32_bf16 v[48:51], v[248:251], v[220:223], v[48:51]
	ds_read_b128 v[248:251], v119 offset:58240
	s_waitcnt lgkmcnt(6)
	v_mfma_f32_16x16x32_bf16 v[48:51], v[224:227], v[60:63], v[48:51]
	ds_read_b128 v[224:227], v119 offset:58304
	s_waitcnt lgkmcnt(6)
	v_mfma_f32_16x16x32_bf16 v[48:51], v[228:231], v[52:55], v[48:51]
	ds_read_b128 v[228:231], v112
	s_waitcnt lgkmcnt(6)
	v_mfma_f32_16x16x32_bf16 v[48:51], v[232:235], v[56:59], v[48:51]
	ds_read_b128 v[232:235], v121 offset:17408
	ds_read_b128 v[96:99], v119 offset:53952
	s_waitcnt lgkmcnt(0)
	v_mfma_f32_16x16x32_bf16 v[48:51], v[96:99], v[44:47], v[48:51]
	s_nop 7
	v_cvt_pk_bf16_f32 v42, v48, v49
	v_cvt_pk_bf16_f32 v43, v50, v51
	v_mfma_f32_16x16x32_bf16 v[36:39], v[236:239], v[216:219], 0
	ds_read_b128 v[216:219], v121 offset:17472
	ds_read_b128 v[236:239], v112 offset:64
	ds_read_b128 v[48:51], v121 offset:42816
	global_store_dwordx2 v[40:41], v[42:43], off offset:64
	s_waitcnt lgkmcnt(0)
	v_mfma_f32_16x16x32_bf16 v[32:35], v[48:51], v[220:223], v[36:39]
	s_nop 3
	v_mfma_f32_16x16x32_bf16 v[32:35], v[244:247], v[60:63], v[32:35]
	ds_read_b128 v[220:223], v121 offset:19712
	v_mfma_f32_16x16x32_bf16 v[32:35], v[252:255], v[52:55], v[32:35]
	ds_read_b128 v[244:247], v121 offset:19776
	v_mfma_f32_16x16x32_bf16 v[32:35], v[248:251], v[56:59], v[32:35]
	ds_read_b128 v[252:255], v112 offset:128
	v_mfma_f32_16x16x32_bf16 v[32:35], v[224:227], v[44:47], v[32:35]
	ds_read_b128 v[248:251], v121 offset:22016
	s_nop 7
	v_cvt_pk_bf16_f32 v32, v32, v33
	v_cvt_pk_bf16_f32 v33, v34, v35
	global_store_dwordx2 v[40:41], v[32:33], off offset:96
	ds_read_b128 v[36:39], v160 offset:35840
	ds_read_b128 v[32:35], v160 offset:35904
	v_pk_mul_f32 v[16:17], v[16:17], v[228:229]
	ds_read_b128 v[224:227], v121 offset:22080
	v_pk_mul_f32 v[18:19], v[18:19], v[230:231]
	s_waitcnt lgkmcnt(2)
	s_nop 0
	v_mfma_f32_16x16x32_bf16 v[16:19], v[232:235], v[36:39], v[16:19]
	ds_read_b128 v[228:231], v112 offset:192
	s_waitcnt lgkmcnt(2)
	v_mfma_f32_16x16x32_bf16 v[16:19], v[216:219], v[32:35], v[16:19]
	ds_read_b128 v[232:235], v121 offset:24320
	v_pk_mul_f32 v[0:1], v[0:1], v[236:237]
	ds_read_b128 v[216:219], v121 offset:24384
	v_pk_mul_f32 v[2:3], v[2:3], v[238:239]
	s_nop 1
	v_mfma_f32_16x16x32_bf16 v[0:3], v[220:223], v[36:39], v[0:3]
	ds_read_b128 v[236:239], v112 offset:256
	v_mfma_f32_16x16x32_bf16 v[0:3], v[244:247], v[32:35], v[0:3]
	ds_read_b128 v[220:223], v121 offset:26624
	v_pk_mul_f32 v[8:9], v[8:9], v[252:253]
	ds_read_b128 v[244:247], v121 offset:26688
	v_pk_mul_f32 v[10:11], v[10:11], v[254:255]
	s_nop 1
	v_mfma_f32_16x16x32_bf16 v[8:11], v[248:251], v[36:39], v[8:11]
	ds_read_b128 v[252:255], v112 offset:320
	s_waitcnt lgkmcnt(7)
	v_mfma_f32_16x16x32_bf16 v[8:11], v[224:227], v[32:35], v[8:11]
	ds_read_b128 v[248:251], v121 offset:28928
	s_waitcnt lgkmcnt(7)
	v_pk_mul_f32 v[4:5], v[4:5], v[228:229]
	ds_read_b128 v[224:227], v121 offset:28992
	v_pk_mul_f32 v[6:7], v[6:7], v[230:231]
	s_waitcnt lgkmcnt(7)
	s_nop 0
	v_mfma_f32_16x16x32_bf16 v[4:7], v[232:235], v[36:39], v[4:7]
	ds_read_b128 v[228:231], v112 offset:384
	s_waitcnt lgkmcnt(7)
	v_mfma_f32_16x16x32_bf16 v[4:7], v[216:219], v[32:35], v[4:7]
	ds_read_b128 v[232:235], v121 offset:31232
	s_waitcnt lgkmcnt(7)
	v_pk_mul_f32 v[20:21], v[20:21], v[236:237]
	ds_read_b128 v[216:219], v121 offset:31296
	v_pk_mul_f32 v[22:23], v[22:23], v[238:239]
	s_waitcnt lgkmcnt(7)
	s_nop 0
	v_mfma_f32_16x16x32_bf16 v[20:23], v[220:223], v[36:39], v[20:23]
	ds_read_b128 v[236:239], v112 offset:448
	s_waitcnt lgkmcnt(7)
	v_mfma_f32_16x16x32_bf16 v[20:23], v[244:247], v[32:35], v[20:23]
	s_waitcnt lgkmcnt(6)
	v_pk_mul_f32 v[12:13], v[12:13], v[252:253]
	v_pk_mul_f32 v[14:15], v[14:15], v[254:255]
	s_waitcnt lgkmcnt(5)
	s_nop 0
	v_mfma_f32_16x16x32_bf16 v[12:15], v[248:251], v[36:39], v[12:15]
	s_waitcnt lgkmcnt(4)
	v_mfma_f32_16x16x32_bf16 v[12:15], v[224:227], v[32:35], v[12:15]
	s_waitcnt lgkmcnt(3)
	v_pk_mul_f32 v[24:25], v[24:25], v[228:229]
	v_pk_mul_f32 v[26:27], v[26:27], v[230:231]
	s_waitcnt lgkmcnt(2)
	s_nop 0
	v_mfma_f32_16x16x32_bf16 v[24:27], v[232:235], v[36:39], v[24:27]
	s_waitcnt lgkmcnt(1)
	v_mfma_f32_16x16x32_bf16 v[24:27], v[216:219], v[32:35], v[24:27]
	s_waitcnt lgkmcnt(0)
	v_pk_mul_f32 v[28:29], v[28:29], v[236:237]
	v_pk_mul_f32 v[30:31], v[30:31], v[238:239]
	ds_read_b128 v[40:43], v121 offset:33536
	s_waitcnt lgkmcnt(0)
	v_mfma_f32_16x16x32_bf16 v[28:31], v[40:43], v[36:39], v[28:31]
	ds_read_b128 v[36:39], v121 offset:33600
	s_waitcnt lgkmcnt(0)
	s_barrier
	v_mfma_f32_16x16x32_bf16 v[28:31], v[36:39], v[32:35], v[28:31]
	s_andn2_b64 exec, exec, s[56:57]
	s_cbranch_execz .LBB0_1466

.LBB0_1476:
	s_or_b64 exec, exec, s[60:61]
	v_sub_f32_e32 v32, v73, v33
	v_exp_f32_e32 v156, v32
	v_sub_f32_e32 v32, v155, v35
	v_exp_f32_e32 v158, v32
	v_mov_b32_e32 v32, v36
	v_mov_b32_e32 v33, v38
	v_mov_b32_e32 v38, v37
	v_pk_mul_f32 v[32:33], v[156:157], v[32:33] op_sel_hi:[0,1]
	v_pk_mul_f32 v[34:35], v[158:159], v[38:39] op_sel_hi:[0,1]
	v_cvt_pk_bf16_f32 v36, v32, v33
	v_cvt_pk_bf16_f32 v32, v34, v35
	v_mov_b32_e32 v34, v40
	v_mov_b32_e32 v35, v42
	v_pk_mul_f32 v[34:35], v[156:157], v[34:35] op_sel_hi:[0,1]
	v_mov_b32_e32 v42, v41
	v_cvt_pk_bf16_f32 v37, v34, v35
	v_mov_b32_e32 v34, v44
	v_mov_b32_e32 v35, v46
	v_mov_b32_e32 v46, v45
	v_pk_mul_f32 v[38:39], v[158:159], v[42:43] op_sel_hi:[0,1]
	v_pk_mul_f32 v[34:35], v[156:157], v[34:35] op_sel_hi:[0,1]
	v_pk_mul_f32 v[40:41], v[158:159], v[46:47] op_sel_hi:[0,1]
	v_cvt_pk_bf16_f32 v33, v38, v39
	v_cvt_pk_bf16_f32 v38, v34, v35
	v_cvt_pk_bf16_f32 v34, v40, v41
	v_mov_b32_e32 v40, v48
	v_mov_b32_e32 v41, v50
	v_pk_mul_f32 v[40:41], v[156:157], v[40:41] op_sel_hi:[0,1]
	v_mov_b32_e32 v50, v49
	v_pk_mul_f32 v[42:43], v[158:159], v[50:51] op_sel_hi:[0,1]
	v_cvt_pk_bf16_f32 v39, v40, v41
	v_mov_b32_e32 v40, v52
	v_mov_b32_e32 v41, v54
	v_mov_b32_e32 v54, v53
	v_cvt_pk_bf16_f32 v35, v42, v43
	v_pk_mul_f32 v[40:41], v[156:157], v[40:41] op_sel_hi:[0,1]
	v_pk_mul_f32 v[42:43], v[158:159], v[54:55] op_sel_hi:[0,1]
	v_cvt_pk_bf16_f32 v44, v40, v41
	v_cvt_pk_bf16_f32 v40, v42, v43
	v_mov_b32_e32 v42, v56
	v_mov_b32_e32 v43, v60
	v_pk_mul_f32 v[42:43], v[156:157], v[42:43] op_sel_hi:[0,1]
	v_mov_b32_e32 v60, v57
	v_cvt_pk_bf16_f32 v45, v42, v43
	v_mov_b32_e32 v42, v92
	v_mov_b32_e32 v43, v94
	v_mov_b32_e32 v94, v93
	v_pk_mul_f32 v[46:47], v[158:159], v[60:61] op_sel_hi:[0,1]
	v_pk_mul_f32 v[42:43], v[156:157], v[42:43] op_sel_hi:[0,1]
	v_pk_mul_f32 v[48:49], v[158:159], v[94:95] op_sel_hi:[0,1]
	v_cvt_pk_bf16_f32 v41, v46, v47
	v_cvt_pk_bf16_f32 v46, v42, v43
	v_cvt_pk_bf16_f32 v42, v48, v49
	v_mov_b32_e32 v48, v62
	v_mov_b32_e32 v49, v58
	v_mov_b32_e32 v58, v63
	v_pk_mul_f32 v[48:49], v[156:157], v[48:49] op_sel_hi:[0,1]
	v_pk_mul_f32 v[50:51], v[158:159], v[58:59] op_sel_hi:[0,1]
	v_cvt_pk_bf16_f32 v47, v48, v49
	v_cvt_pk_bf16_f32 v43, v50, v51
	s_waitcnt lgkmcnt(0)
	s_barrier
	s_waitcnt lgkmcnt(0)
	ds_read_b128 v[216:219], v105
	v_add_u32_e32 v52, v107, v109
	v_add_u32_e32 v60, v107, v104
	v_cmp_eq_u32_e32 vcc, s75, v132
	v_lshl_add_u64 v[86:87], v[86:87], 0, s[56:57]
	s_waitcnt lgkmcnt(0)
	v_pk_mul_f32 v[48:49], v[12:13], v[216:217]
	v_pk_mul_f32 v[50:51], v[14:15], v[218:219]
	v_cvt_pk_bf16_f32 v48, v48, v49
	v_cvt_pk_bf16_f32 v49, v50, v51
	ds_write_b64 v52, v[48:49] offset:45056
	ds_read_b128 v[220:223], v105 offset:64
	v_lshl_add_u64 v[88:89], v[88:89], 0, s[56:57]
	v_lshl_add_u64 v[90:91], v[90:91], 0, s[56:57]
	s_or_b64 s[58:59], vcc, s[58:59]
	s_waitcnt lgkmcnt(0)
	v_pk_mul_f32 v[48:49], v[0:1], v[220:221]
	v_pk_mul_f32 v[50:51], v[2:3], v[222:223]
	v_cvt_pk_bf16_f32 v48, v48, v49
	v_cvt_pk_bf16_f32 v49, v50, v51
	ds_write_b64 v113, v[48:49] offset:45056
	ds_read_b128 v[224:227], v105 offset:128
	s_waitcnt lgkmcnt(0)
	v_pk_mul_f32 v[48:49], v[8:9], v[224:225]
	v_pk_mul_f32 v[50:51], v[10:11], v[226:227]
	v_cvt_pk_bf16_f32 v48, v48, v49
	v_cvt_pk_bf16_f32 v49, v50, v51
	ds_write_b64 v114, v[48:49] offset:45056
	ds_read_b128 v[228:231], v105 offset:192
	s_waitcnt lgkmcnt(0)
	v_pk_mul_f32 v[48:49], v[4:5], v[228:229]
	v_pk_mul_f32 v[50:51], v[6:7], v[230:231]
	v_cvt_pk_bf16_f32 v48, v48, v49
	v_cvt_pk_bf16_f32 v49, v50, v51
	ds_write_b64 v115, v[48:49] offset:45056
	ds_read_b128 v[232:235], v105 offset:256
	s_waitcnt lgkmcnt(0)
	v_pk_mul_f32 v[48:49], v[20:21], v[232:233]
	v_pk_mul_f32 v[50:51], v[22:23], v[234:235]
	v_cvt_pk_bf16_f32 v48, v48, v49
	v_cvt_pk_bf16_f32 v49, v50, v51
	ds_write_b64 v52, v[48:49] offset:45184
	ds_read_b128 v[236:239], v105 offset:320
	s_waitcnt lgkmcnt(0)
	v_pk_mul_f32 v[48:49], v[16:17], v[236:237]
	v_pk_mul_f32 v[50:51], v[18:19], v[238:239]
	v_cvt_pk_bf16_f32 v48, v48, v49
	v_cvt_pk_bf16_f32 v49, v50, v51
	ds_write_b64 v52, v[48:49] offset:45216
	ds_read_b128 v[244:247], v105 offset:384
	s_waitcnt lgkmcnt(0)
	v_pk_mul_f32 v[48:49], v[24:25], v[244:245]
	v_pk_mul_f32 v[50:51], v[26:27], v[246:247]
	v_cvt_pk_bf16_f32 v48, v48, v49
	v_cvt_pk_bf16_f32 v49, v50, v51
	ds_write_b64 v52, v[48:49] offset:45248
	ds_read_b128 v[248:251], v105 offset:448
	s_waitcnt lgkmcnt(0)
	v_pk_mul_f32 v[48:49], v[28:29], v[248:249]
	v_pk_mul_f32 v[50:51], v[30:31], v[250:251]
	v_cvt_pk_bf16_f32 v48, v48, v49
	v_cvt_pk_bf16_f32 v49, v50, v51
	ds_write_b64 v52, v[48:49] offset:45280
	ds_read_b128 v[252:255], v116 offset:17408
	ds_read_b128 v[216:219], v116 offset:17472
	ds_read_b128 v[220:223], v116 offset:21824
	ds_read_b128 v[224:227], v116 offset:17536
	ds_read_b128 v[228:231], v116 offset:17600
	ds_read_b128 v[232:235], v116 offset:21760
	ds_read_b128 v[236:239], v116 offset:21888
	ds_read_b128 v[244:247], v116 offset:21952
	ds_read_b128 v[48:51], v60
	ds_read_b128 v[52:55], v60 offset:64
	ds_read_b128 v[56:59], v60 offset:128
	ds_read_b128 v[60:63], v60 offset:192
	s_waitcnt lgkmcnt(3)
	v_mfma_f32_16x16x32_bf16 v[92:95], v[252:255], v[48:51], 0
	ds_read_b128 v[248:251], v116 offset:26176
	s_waitcnt lgkmcnt(3)
	v_mfma_f32_16x16x32_bf16 v[92:95], v[216:219], v[52:55], v[92:95]
	ds_read_b128 v[252:255], v116 offset:26112
	s_waitcnt lgkmcnt(3)
	v_mfma_f32_16x16x32_bf16 v[92:95], v[224:227], v[56:59], v[92:95]
	ds_read_b128 v[216:219], v116 offset:26240
	s_waitcnt lgkmcnt(3)
	v_mfma_f32_16x16x32_bf16 v[92:95], v[228:231], v[60:63], v[92:95]
	ds_read_b128 v[224:227], v116 offset:26304
	s_nop 6
	v_cndmask_b32_e64 v73, v92, 0, s[4:5]
	v_mfma_f32_16x16x32_bf16 v[156:159], v[232:235], v[48:51], 0
	ds_read_b128 v[228:231], v116 offset:30528
	v_cndmask_b32_e64 v92, 0, v93, s[6:7]
	v_cndmask_b32_e64 v93, v94, 0, s[8:9]
	v_cndmask_b32_e64 v94, v95, 0, s[10:11]
	v_mfma_f32_16x16x32_bf16 v[156:159], v[220:223], v[52:55], v[156:159]
	ds_read_b128 v[232:235], v116 offset:30464
	v_cvt_pk_bf16_f32 v92, v73, v92
	v_cvt_pk_bf16_f32 v93, v93, v94
	v_mfma_f32_16x16x32_bf16 v[156:159], v[236:239], v[56:59], v[156:159]
	ds_read_b128 v[220:223], v116 offset:30592
	v_mfma_f32_16x16x32_bf16 v[156:159], v[244:247], v[60:63], v[156:159]
	s_nop 6
	s_nop 0
	v_cndmask_b32_e64 v73, v156, 0, s[12:13]
	v_cndmask_b32_e64 v94, v157, 0, s[14:15]
	v_cndmask_b32_e64 v95, v158, 0, s[16:17]
	v_cndmask_b32_e64 v155, v159, 0, s[18:19]
	s_waitcnt lgkmcnt(5)
	v_mfma_f32_16x16x32_bf16 v[156:159], v[252:255], v[48:51], 0
	v_cvt_pk_bf16_f32 v94, v73, v94
	v_cvt_pk_bf16_f32 v95, v95, v155
	v_mfma_f32_16x16x32_bf16 v[156:159], v[248:251], v[52:55], v[156:159]
	s_waitcnt lgkmcnt(4)
	v_mfma_f32_16x16x32_bf16 v[156:159], v[216:219], v[56:59], v[156:159]
	s_waitcnt lgkmcnt(3)
	v_mfma_f32_16x16x32_bf16 v[156:159], v[224:227], v[60:63], v[156:159]
	s_nop 6
	s_nop 0
	v_cndmask_b32_e64 v73, v156, 0, s[20:21]
	v_cndmask_b32_e64 v155, v157, 0, s[22:23]
	v_cndmask_b32_e64 v156, v158, 0, s[24:25]
	v_cndmask_b32_e64 v157, v159, 0, s[26:27]
	v_cvt_pk_bf16_f32 v165, v156, v157
	s_waitcnt lgkmcnt(1)
	v_mfma_f32_16x16x32_bf16 v[156:159], v[232:235], v[48:51], 0
	v_cvt_pk_bf16_f32 v164, v73, v155
	v_mfma_f32_16x16x32_bf16 v[156:159], v[228:231], v[52:55], v[156:159]
	s_waitcnt lgkmcnt(0)
	v_mfma_f32_16x16x32_bf16 v[156:159], v[220:223], v[56:59], v[156:159]
	ds_read_b128 v[160:163], v116 offset:30656
	s_waitcnt lgkmcnt(0)
	s_barrier
	v_mfma_f32_16x16x32_bf16 v[156:159], v[160:163], v[60:63], v[156:159]
	s_nop 7
	v_cndmask_b32_e64 v73, v156, 0, s[28:29]
	v_cndmask_b32_e64 v155, v157, 0, s[30:31]
	v_cvt_pk_bf16_f32 v156, v73, v155
	v_add_u32_e32 v73, v108, v109
	v_cndmask_b32_e64 v157, v158, 0, s[34:35]
	v_cndmask_b32_e64 v158, v159, 0, s[36:37]
	v_add_u32_e32 v73, 0xf000, v73
	v_cvt_pk_bf16_f32 v157, v157, v158
	ds_write2_b64 v73, v[92:93], v[94:95] offset0:128 offset1:132
	ds_write2_b64 v73, v[164:165], v[156:157] offset0:136 offset1:140
	ds_write_b128 v117, v[36:39] offset:17408
	ds_write_b128 v117, v[44:47] offset:17424
	ds_write_b128 v117, v[32:35] offset:17552
	ds_write_b128 v117, v[40:43] offset:17568
	v_add_u32_e32 v46, v108, v104
	s_waitcnt lgkmcnt(0)
	s_barrier
	s_waitcnt lgkmcnt(0)
	ds_read_b128 v[216:219], v46 offset:62464
	ds_read_b128 v[220:223], v46 offset:62528
	ds_read_b128 v[224:227], v118 offset:35840
	ds_read_b128 v[228:231], v118 offset:35904
	ds_read_b128 v[232:235], v116 offset:45056
	ds_read_b128 v[236:239], v116 offset:45120
	ds_read_b128 v[244:247], v116 offset:45184
	ds_read_b128 v[248:251], v116 offset:45248
	s_waitcnt lgkmcnt(5)
	v_mfma_f32_16x16x32_bf16 v[42:45], v[224:227], v[216:219], 0
	ds_read_b128 v[252:255], v118 offset:38208
	ds_read_b128 v[224:227], v118 offset:38144
	v_lshlrev_b64 v[32:33], 11, v[64:65]
	v_lshl_add_u64 v[32:33], v[84:85], 0, v[32:33]
	v_add_u32_e32 v64, 64, v64
	s_waitcnt lgkmcnt(6)
	v_mfma_f32_16x16x32_bf16 v[42:45], v[228:231], v[220:223], v[42:45]
	ds_read_b128 v[228:231], v116 offset:49408
	s_waitcnt lgkmcnt(6)
	v_mfma_f32_16x16x32_bf16 v[42:45], v[232:235], v[48:51], v[42:45]
	ds_read_b128 v[232:235], v116 offset:49472
	s_waitcnt lgkmcnt(6)
	v_mfma_f32_16x16x32_bf16 v[42:45], v[236:239], v[52:55], v[42:45]
	ds_read_b128 v[236:239], v116 offset:49536
	s_waitcnt lgkmcnt(6)
	v_mfma_f32_16x16x32_bf16 v[42:45], v[244:247], v[56:59], v[42:45]
	ds_read_b128 v[244:247], v116 offset:49600
	s_waitcnt lgkmcnt(6)
	v_mfma_f32_16x16x32_bf16 v[42:45], v[248:251], v[60:63], v[42:45]
	ds_read_b128 v[248:251], v118 offset:40512
	s_nop 6
	v_cvt_pk_bf16_f32 v42, v42, v43
	v_cvt_pk_bf16_f32 v43, v44, v45
	global_store_dwordx2 v[32:33], v[42:43], off
	s_waitcnt lgkmcnt(5)
	v_mfma_f32_16x16x32_bf16 v[42:45], v[224:227], v[216:219], 0
	ds_read_b128 v[224:227], v118 offset:40448
	v_mfma_f32_16x16x32_bf16 v[42:45], v[252:255], v[220:223], v[42:45]
	ds_read_b128 v[252:255], v116 offset:53760
	s_waitcnt lgkmcnt(6)
	v_mfma_f32_16x16x32_bf16 v[42:45], v[228:231], v[48:51], v[42:45]
	ds_read_b128 v[228:231], v116 offset:53824
	s_waitcnt lgkmcnt(6)
	v_mfma_f32_16x16x32_bf16 v[42:45], v[232:235], v[52:55], v[42:45]
	ds_read_b128 v[232:235], v116 offset:53888
	s_waitcnt lgkmcnt(6)
	v_mfma_f32_16x16x32_bf16 v[42:45], v[236:239], v[56:59], v[42:45]
	ds_read_b128 v[236:239], v118 offset:42752
	s_waitcnt lgkmcnt(6)
	v_mfma_f32_16x16x32_bf16 v[42:45], v[244:247], v[60:63], v[42:45]
	ds_read_b128 v[244:247], v116 offset:58112
	s_nop 6
	v_cvt_pk_bf16_f32 v42, v42, v43
	v_cvt_pk_bf16_f32 v43, v44, v45
	global_store_dwordx2 v[32:33], v[42:43], off offset:32
	s_waitcnt lgkmcnt(5)
	v_mfma_f32_16x16x32_bf16 v[42:45], v[224:227], v[216:219], 0
	ds_read_b128 v[224:227], v116 offset:58176
	v_mfma_f32_16x16x32_bf16 v[42:45], v[248:251], v[220:223], v[42:45]
	ds_read_b128 v[248:251], v116 offset:58240
	s_waitcnt lgkmcnt(6)
	v_mfma_f32_16x16x32_bf16 v[42:45], v[252:255], v[48:51], v[42:45]
	ds_read_b128 v[252:255], v116 offset:58304
	s_waitcnt lgkmcnt(6)
	v_mfma_f32_16x16x32_bf16 v[42:45], v[228:231], v[52:55], v[42:45]
	ds_read_b128 v[228:231], v110
	s_waitcnt lgkmcnt(6)
	v_mfma_f32_16x16x32_bf16 v[42:45], v[232:235], v[56:59], v[42:45]
	ds_read_b128 v[232:235], v118 offset:17408
	ds_read_b128 v[92:95], v116 offset:53952
	s_waitcnt lgkmcnt(0)
	v_mfma_f32_16x16x32_bf16 v[42:45], v[92:95], v[60:63], v[42:45]
	s_nop 7
	v_cvt_pk_bf16_f32 v42, v42, v43
	v_cvt_pk_bf16_f32 v43, v44, v45
	global_store_dwordx2 v[32:33], v[42:43], off offset:64
	v_mfma_f32_16x16x32_bf16 v[34:37], v[236:239], v[216:219], 0
	ds_read_b128 v[216:219], v118 offset:17472
	ds_read_b128 v[236:239], v110 offset:64
	ds_read_b128 v[42:45], v118 offset:42816
	s_waitcnt lgkmcnt(0)
	v_mfma_f32_16x16x32_bf16 v[34:37], v[42:45], v[220:223], v[34:37]
	v_mfma_f32_16x16x32_bf16 v[34:37], v[244:247], v[48:51], v[34:37]
	ds_read_b128 v[220:223], v118 offset:19712
	v_mfma_f32_16x16x32_bf16 v[34:37], v[224:227], v[52:55], v[34:37]
	ds_read_b128 v[244:247], v118 offset:19776
	v_mfma_f32_16x16x32_bf16 v[34:37], v[248:251], v[56:59], v[34:37]
	ds_read_b128 v[224:227], v110 offset:128
	v_mfma_f32_16x16x32_bf16 v[34:37], v[252:255], v[60:63], v[34:37]
	ds_read_b128 v[248:251], v118 offset:22016
	s_nop 7
	v_cvt_pk_bf16_f32 v34, v34, v35
	v_cvt_pk_bf16_f32 v35, v36, v37
	global_store_dwordx2 v[32:33], v[34:35], off offset:96
	ds_read_b128 v[36:39], v46 offset:35840
	ds_read_b128 v[32:35], v46 offset:35904
	v_pk_mul_f32 v[12:13], v[12:13], v[228:229]
	ds_read_b128 v[252:255], v118 offset:22080
	v_pk_mul_f32 v[14:15], v[14:15], v[230:231]
	s_waitcnt lgkmcnt(2)
	s_nop 0
	v_mfma_f32_16x16x32_bf16 v[12:15], v[232:235], v[36:39], v[12:15]
	ds_read_b128 v[228:231], v110 offset:192
	s_waitcnt lgkmcnt(2)
	v_mfma_f32_16x16x32_bf16 v[12:15], v[216:219], v[32:35], v[12:15]
	ds_read_b128 v[232:235], v118 offset:24320
	v_pk_mul_f32 v[0:1], v[0:1], v[236:237]
	ds_read_b128 v[216:219], v118 offset:24384
	v_pk_mul_f32 v[2:3], v[2:3], v[238:239]
	s_nop 1
	v_mfma_f32_16x16x32_bf16 v[0:3], v[220:223], v[36:39], v[0:3]
	ds_read_b128 v[236:239], v110 offset:256
	v_mfma_f32_16x16x32_bf16 v[0:3], v[244:247], v[32:35], v[0:3]
	ds_read_b128 v[220:223], v118 offset:26624
	v_pk_mul_f32 v[8:9], v[8:9], v[224:225]
	ds_read_b128 v[244:247], v118 offset:26688
	v_pk_mul_f32 v[10:11], v[10:11], v[226:227]
	s_nop 1
	v_mfma_f32_16x16x32_bf16 v[8:11], v[248:251], v[36:39], v[8:11]
	ds_read_b128 v[224:227], v110 offset:320
	s_waitcnt lgkmcnt(7)
	v_mfma_f32_16x16x32_bf16 v[8:11], v[252:255], v[32:35], v[8:11]
	ds_read_b128 v[248:251], v118 offset:28928
	s_waitcnt lgkmcnt(7)
	v_pk_mul_f32 v[4:5], v[4:5], v[228:229]
	ds_read_b128 v[252:255], v118 offset:28992
	v_pk_mul_f32 v[6:7], v[6:7], v[230:231]
	s_waitcnt lgkmcnt(7)
	s_nop 0
	v_mfma_f32_16x16x32_bf16 v[4:7], v[232:235], v[36:39], v[4:7]
	ds_read_b128 v[228:231], v110 offset:384
	s_waitcnt lgkmcnt(7)
	v_mfma_f32_16x16x32_bf16 v[4:7], v[216:219], v[32:35], v[4:7]
	ds_read_b128 v[232:235], v118 offset:31232
	s_waitcnt lgkmcnt(7)
	v_pk_mul_f32 v[20:21], v[20:21], v[236:237]
	ds_read_b128 v[216:219], v118 offset:31296
	v_pk_mul_f32 v[22:23], v[22:23], v[238:239]
	s_waitcnt lgkmcnt(7)
	s_nop 0
	v_mfma_f32_16x16x32_bf16 v[20:23], v[220:223], v[36:39], v[20:23]
	ds_read_b128 v[236:239], v110 offset:448
	s_waitcnt lgkmcnt(7)
	v_mfma_f32_16x16x32_bf16 v[20:23], v[244:247], v[32:35], v[20:23]
	s_waitcnt lgkmcnt(6)
	v_pk_mul_f32 v[16:17], v[16:17], v[224:225]
	v_pk_mul_f32 v[18:19], v[18:19], v[226:227]
	s_waitcnt lgkmcnt(5)
	s_nop 0
	v_mfma_f32_16x16x32_bf16 v[16:19], v[248:251], v[36:39], v[16:19]
	s_waitcnt lgkmcnt(4)
	v_mfma_f32_16x16x32_bf16 v[16:19], v[252:255], v[32:35], v[16:19]
	s_waitcnt lgkmcnt(3)
	v_pk_mul_f32 v[24:25], v[24:25], v[228:229]
	v_pk_mul_f32 v[26:27], v[26:27], v[230:231]
	s_waitcnt lgkmcnt(2)
	s_nop 0
	v_mfma_f32_16x16x32_bf16 v[24:27], v[232:235], v[36:39], v[24:27]
	s_waitcnt lgkmcnt(1)
	v_mfma_f32_16x16x32_bf16 v[24:27], v[216:219], v[32:35], v[24:27]
	s_waitcnt lgkmcnt(0)
	v_pk_mul_f32 v[28:29], v[28:29], v[236:237]
	v_pk_mul_f32 v[30:31], v[30:31], v[238:239]
	ds_read_b128 v[40:43], v118 offset:33536
	s_waitcnt lgkmcnt(0)
	v_mfma_f32_16x16x32_bf16 v[28:31], v[40:43], v[36:39], v[28:31]
	ds_read_b128 v[36:39], v118 offset:33600
	s_waitcnt lgkmcnt(0)
	s_barrier
	v_mfma_f32_16x16x32_bf16 v[28:31], v[36:39], v[32:35], v[28:31]
	s_andn2_b64 exec, exec, s[58:59]
	s_cbranch_execz .LBB0_1481

.LBB0_1493:
	s_or_b64 exec, exec, s[54:55]
	v_sub_f32_e32 v34, v56, v35
	v_exp_f32_e32 v98, v34
	v_sub_f32_e32 v34, v77, v39
	v_exp_f32_e32 v56, v34
	v_mov_b32_e32 v34, v44
	v_mov_b32_e32 v35, v40
	v_mov_b32_e32 v40, v45
	s_waitcnt lgkmcnt(0)
	s_barrier
	s_waitcnt lgkmcnt(0)
	ds_read_b128 v[216:219], v114
	v_add_u32_e32 v197, v115, v117
	v_pk_mul_f32 v[34:35], v[98:99], v[34:35] op_sel_hi:[0,1]
	v_pk_mul_f32 v[40:41], v[56:57], v[40:41] op_sel_hi:[0,1]
	v_cvt_pk_bf16_f32 v39, v34, v35
	s_waitcnt lgkmcnt(0)
	v_pk_mul_f32 v[44:45], v[0:1], v[216:217]
	v_pk_mul_f32 v[46:47], v[2:3], v[218:219]
	v_cvt_pk_bf16_f32 v44, v44, v45
	v_cvt_pk_bf16_f32 v45, v46, v47
	ds_write_b64 v197, v[44:45] offset:45056
	ds_read_b128 v[220:223], v114 offset:64
	v_cvt_pk_bf16_f32 v35, v40, v41
	v_mov_b32_e32 v41, v32
	v_mov_b32_e32 v32, v43
	v_pk_mul_f32 v[32:33], v[56:57], v[32:33] op_sel_hi:[0,1]
	v_cvt_pk_bf16_f32 v34, v32, v33
	s_waitcnt lgkmcnt(0)
	v_pk_mul_f32 v[32:33], v[4:5], v[220:221]
	v_pk_mul_f32 v[48:49], v[6:7], v[222:223]
	v_cvt_pk_bf16_f32 v32, v32, v33
	v_cvt_pk_bf16_f32 v33, v48, v49
	ds_write_b64 v143, v[32:33] offset:45056
	ds_read_b128 v[224:227], v114 offset:128
	v_mov_b32_e32 v40, v42
	v_pk_mul_f32 v[54:55], v[98:99], v[40:41] op_sel_hi:[0,1]
	v_cvt_pk_bf16_f32 v38, v54, v55
	v_mov_b32_e32 v32, v52
	s_waitcnt lgkmcnt(0)
	v_pk_mul_f32 v[54:55], v[12:13], v[224:225]
	v_pk_mul_f32 v[198:199], v[14:15], v[226:227]
	v_cvt_pk_bf16_f32 v54, v54, v55
	v_cvt_pk_bf16_f32 v55, v198, v199
	ds_write_b64 v144, v[54:55] offset:45056
	ds_read_b128 v[228:231], v114 offset:192
	v_mov_b32_e32 v33, v36
	v_pk_mul_f32 v[32:33], v[98:99], v[32:33] op_sel_hi:[0,1]
	v_mov_b32_e32 v36, v53
	v_pk_mul_f32 v[202:203], v[56:57], v[36:37] op_sel_hi:[0,1]
	v_cvt_pk_bf16_f32 v37, v32, v33
	s_waitcnt lgkmcnt(0)
	v_pk_mul_f32 v[32:33], v[8:9], v[228:229]
	v_pk_mul_f32 v[198:199], v[10:11], v[230:231]
	v_cvt_pk_bf16_f32 v32, v32, v33
	v_cvt_pk_bf16_f32 v33, v198, v199
	ds_write_b64 v145, v[32:33] offset:45056
	ds_read_b128 v[232:235], v114 offset:256
	v_cvt_pk_bf16_f32 v33, v202, v203
	v_mov_b32_e32 v203, v78
	v_mov_b32_e32 v78, v81
	v_pk_mul_f32 v[78:79], v[56:57], v[78:79] op_sel_hi:[0,1]
	s_waitcnt lgkmcnt(0)
	v_pk_mul_f32 v[198:199], v[20:21], v[232:233]
	v_pk_mul_f32 v[200:201], v[22:23], v[234:235]
	v_cvt_pk_bf16_f32 v198, v198, v199
	v_cvt_pk_bf16_f32 v199, v200, v201
	ds_write_b64 v197, v[198:199] offset:45184
	ds_read_b128 v[236:239], v114 offset:320
	v_mov_b32_e32 v202, v80
	v_cvt_pk_bf16_f32 v32, v78, v79
	v_add_u32_e32 v77, v115, v113
	v_pk_mul_f32 v[202:203], v[98:99], v[202:203] op_sel_hi:[0,1]
	s_waitcnt lgkmcnt(0)
	v_pk_mul_f32 v[78:79], v[16:17], v[236:237]
	v_pk_mul_f32 v[80:81], v[18:19], v[238:239]
	v_cvt_pk_bf16_f32 v78, v78, v79
	v_cvt_pk_bf16_f32 v79, v80, v81
	ds_write_b64 v197, v[78:79] offset:45216
	ds_read_b128 v[244:247], v114 offset:384
	ds_read_b128 v[40:43], v77
	ds_read_b128 v[44:47], v77 offset:64
	v_cvt_pk_bf16_f32 v36, v202, v203
	v_mov_b32_e32 v199, v82
	s_waitcnt lgkmcnt(2)
	v_pk_mul_f32 v[78:79], v[28:29], v[244:245]
	v_pk_mul_f32 v[80:81], v[30:31], v[246:247]
	v_cvt_pk_bf16_f32 v78, v78, v79
	v_cvt_pk_bf16_f32 v79, v80, v81
	ds_write_b64 v197, v[78:79] offset:45248
	ds_read_b128 v[248:251], v114 offset:448
	v_mov_b32_e32 v82, v85
	v_mov_b32_e32 v198, v84
	v_pk_mul_f32 v[84:85], v[56:57], v[82:83] op_sel_hi:[0,1]
	v_cvt_pk_bf16_f32 v201, v84, v85
	s_waitcnt lgkmcnt(0)
	v_pk_mul_f32 v[78:79], v[24:25], v[248:249]
	v_pk_mul_f32 v[80:81], v[26:27], v[250:251]
	v_cvt_pk_bf16_f32 v78, v78, v79
	v_cvt_pk_bf16_f32 v79, v80, v81
	ds_write_b64 v197, v[78:79] offset:45280
	ds_read_b128 v[252:255], v146 offset:17408
	ds_read_b128 v[216:219], v146 offset:17472
	ds_read_b128 v[220:223], v146 offset:17536
	ds_read_b128 v[224:227], v146 offset:17600
	ds_read_b128 v[228:231], v146 offset:21760
	ds_read_b128 v[232:235], v146 offset:21824
	ds_read_b128 v[236:239], v146 offset:21888
	ds_read_b128 v[244:247], v146 offset:26112
	v_mov_b32_e32 v84, v88
	v_mov_b32_e32 v85, v86
	v_mov_b32_e32 v86, v89
	v_pk_mul_f32 v[84:85], v[98:99], v[84:85] op_sel_hi:[0,1]
	v_pk_mul_f32 v[86:87], v[56:57], v[86:87] op_sel_hi:[0,1]
	v_cvt_pk_bf16_f32 v82, v84, v85
	v_cvt_pk_bf16_f32 v200, v86, v87
	s_waitcnt lgkmcnt(7)
	v_mfma_f32_16x16x32_bf16 v[78:81], v[252:255], v[40:43], 0
	ds_read_b128 v[248:251], v146 offset:26176
	ds_read_b128 v[48:51], v77 offset:128
	ds_read_b128 v[52:55], v77 offset:192
	v_mov_b32_e32 v88, v92
	s_waitcnt lgkmcnt(9)
	v_mfma_f32_16x16x32_bf16 v[78:81], v[216:219], v[44:47], v[78:81]
	ds_read_b128 v[252:255], v146 offset:26240
	v_mov_b32_e32 v89, v90
	v_pk_mul_f32 v[88:89], v[98:99], v[88:89] op_sel_hi:[0,1]
	v_mov_b32_e32 v90, v93
	s_waitcnt lgkmcnt(2)
	v_mfma_f32_16x16x32_bf16 v[84:87], v[220:223], v[48:51], v[78:81]
	ds_read_b128 v[216:219], v146 offset:26304
	v_mul_f32_e64 v198, v98, v198
	v_mul_f32_e64 v199, v98, v199
	v_cvt_pk_bf16_f32 v83, v198, v199
	ds_read_b128 v[210:213], v146 offset:21952
	v_pk_mul_f32 v[78:79], v[56:57], v[90:91] op_sel_hi:[0,1]
	v_cvt_pk_bf16_f32 v81, v88, v89
	s_waitcnt lgkmcnt(3)
	v_mfma_f32_16x16x32_bf16 v[84:87], v[224:227], v[52:55], v[84:87]
	ds_read_b128 v[220:223], v146 offset:30464
	v_cvt_pk_bf16_f32 v199, v78, v79
	v_mov_b32_e32 v79, v94
	v_mov_b32_e32 v94, v97
	v_mov_b32_e32 v78, v96
	v_mfma_f32_16x16x32_bf16 v[202:205], v[228:231], v[40:43], 0
	ds_read_b128 v[224:227], v146 offset:30592
	v_mul_f32_e64 v96, v56, v94
	v_mul_f32_e64 v97, v56, v95
	v_pk_mul_f32 v[78:79], v[98:99], v[78:79] op_sel_hi:[0,1]
	v_mfma_f32_16x16x32_bf16 v[88:91], v[232:235], v[44:47], v[202:205]
	v_cvt_pk_bf16_f32 v80, v78, v79
	v_cvt_pk_bf16_f32 v198, v96, v97
	v_cndmask_b32_e64 v56, v84, 0, s[4:5]
	v_mfma_f32_16x16x32_bf16 v[88:91], v[236:239], v[48:51], v[88:91]
	v_cndmask_b32_e64 v77, v85, 0, s[10:11]
	v_cndmask_b32_e64 v79, v86, 0, s[12:13]
	v_mfma_f32_16x16x32_bf16 v[92:95], v[244:247], v[40:43], 0
	v_cndmask_b32_e64 v96, v87, 0, s[14:15]
	v_cvt_pk_bf16_f32 v78, v56, v77
	v_mfma_f32_16x16x32_bf16 v[92:95], v[248:251], v[44:47], v[92:95]
	v_cvt_pk_bf16_f32 v79, v79, v96
	v_add_u32_e32 v74, -1, v74
	s_waitcnt lgkmcnt(2)
	v_mfma_f32_16x16x32_bf16 v[88:91], v[210:213], v[52:55], v[88:91]
	s_add_i32 s66, s66, 1
	v_mfma_f32_16x16x32_bf16 v[92:95], v[252:255], v[48:51], v[92:95]
	ds_read_b128 v[206:209], v146 offset:30528
	s_nop 4
	v_cndmask_b32_e64 v56, v88, 0, s[16:17]
	v_cndmask_b32_e64 v77, v89, 0, s[18:19]
	v_cndmask_b32_e64 v97, v90, 0, s[20:21]
	v_cndmask_b32_e64 v98, v91, 0, s[22:23]
	v_mfma_f32_16x16x32_bf16 v[84:87], v[216:219], v[52:55], v[92:95]
	v_cvt_pk_bf16_f32 v96, v56, v77
	v_cvt_pk_bf16_f32 v97, v97, v98
	s_waitcnt lgkmcnt(2)
	v_mfma_f32_16x16x32_bf16 v[92:95], v[220:223], v[40:43], 0
	ds_read_b128 v[202:205], v146 offset:30656
	s_nop 2
	v_cndmask_b32_e64 v56, v84, 0, s[24:25]
	v_cndmask_b32_e64 v77, v85, 0, s[26:27]
	s_waitcnt lgkmcnt(1)
	v_mfma_f32_16x16x32_bf16 v[92:95], v[206:209], v[44:47], v[92:95]
	v_cndmask_b32_e64 v84, v86, 0, s[28:29]
	v_cndmask_b32_e64 v85, v87, 0, s[30:31]
	v_mfma_f32_16x16x32_bf16 v[88:91], v[224:227], v[48:51], v[92:95]
	s_barrier
	s_nop 2
	s_nop 0
	v_cvt_pk_bf16_f32 v93, v84, v85
	v_mfma_f32_16x16x32_bf16 v[84:87], v[202:205], v[52:55], v[88:91]
	v_cvt_pk_bf16_f32 v92, v56, v77
	s_nop 6
	v_cndmask_b32_e64 v56, v84, 0, s[34:35]
	v_cndmask_b32_e64 v77, v85, 0, s[36:37]
	v_cvt_pk_bf16_f32 v84, v56, v77
	v_add_u32_e32 v56, v116, v117
	v_cndmask_b32_e64 v85, v86, 0, s[38:39]
	v_cndmask_b32_e64 v86, v87, 0, s[40:41]
	v_add_u32_e32 v56, 0xf000, v56
	v_cvt_pk_bf16_f32 v85, v85, v86
	ds_write2_b64 v56, v[78:79], v[96:97] offset0:128 offset1:132
	ds_write2_b64 v56, v[92:93], v[84:85] offset0:136 offset1:140
	v_add_u32_e32 v56, v118, v119
	ds_write_b128 v56, v[80:83] offset:17408
	ds_write_b128 v56, v[36:39] offset:17424
	ds_write_b128 v56, v[198:201] offset:17552
	ds_write_b128 v56, v[32:35] offset:17568
	s_waitcnt lgkmcnt(0)
	s_barrier
	s_waitcnt lgkmcnt(0)
	ds_read_b128 v[216:219], v147 offset:35840
	ds_read_b128 v[220:223], v147 offset:35904
	ds_read_b128 v[224:227], v146 offset:45056
	ds_read_b128 v[228:231], v146 offset:49408
	ds_read_b128 v[232:235], v146 offset:53760
	ds_read_b128 v[236:239], v146 offset:45120
	ds_read_b128 v[244:247], v146 offset:45184
	ds_read_b128 v[248:251], v146 offset:45248
	v_add_u32_e32 v77, v116, v113
	ds_read_b128 v[78:81], v77 offset:62464
	ds_read_b128 v[82:85], v77 offset:62528
	s_waitcnt lgkmcnt(1)
	v_mfma_f32_16x16x32_bf16 v[32:35], v[216:219], v[78:81], 0
	ds_read_b128 v[252:255], v147 offset:38144
	s_waitcnt lgkmcnt(1)
	v_mfma_f32_16x16x32_bf16 v[32:35], v[220:223], v[82:85], v[32:35]
	ds_read_b128 v[216:219], v147 offset:38208
	v_ashrrev_i32_e32 v56, 9, v65
	v_cmp_gt_i32_e32 vcc, 32, v56
	v_mfma_f32_16x16x32_bf16 v[32:35], v[224:227], v[40:43], v[32:35]
	ds_read_b128 v[220:223], v146 offset:49472
	v_subrev_u32_e32 v65, 64, v65
	v_mfma_f32_16x16x32_bf16 v[32:35], v[236:239], v[44:47], v[32:35]
	ds_read_b128 v[224:227], v146 offset:49536
	v_mfma_f32_16x16x32_bf16 v[32:35], v[244:247], v[48:51], v[32:35]
	ds_read_b128 v[236:239], v146 offset:49600
	v_mfma_f32_16x16x32_bf16 v[32:35], v[248:251], v[52:55], v[32:35]
	ds_read_b128 v[244:247], v147 offset:40448
	s_waitcnt lgkmcnt(5)
	v_mfma_f32_16x16x32_bf16 v[86:89], v[252:255], v[78:81], 0
	ds_read_b128 v[248:251], v147 offset:40512
	s_waitcnt lgkmcnt(5)
	v_mfma_f32_16x16x32_bf16 v[36:39], v[216:219], v[82:85], v[86:89]
	ds_read_b128 v[252:255], v146 offset:53824
	s_nop 6
	v_mfma_f32_16x16x32_bf16 v[36:39], v[228:231], v[40:43], v[36:39]
	ds_read_b128 v[216:219], v146 offset:53888
	s_waitcnt lgkmcnt(6)
	v_mfma_f32_16x16x32_bf16 v[36:39], v[220:223], v[44:47], v[36:39]
	ds_read_b128 v[228:231], v146 offset:53952
	s_waitcnt lgkmcnt(6)
	v_mfma_f32_16x16x32_bf16 v[36:39], v[224:227], v[48:51], v[36:39]
	ds_read_b128 v[220:223], v147 offset:42752
	s_waitcnt lgkmcnt(6)
	v_mfma_f32_16x16x32_bf16 v[36:39], v[236:239], v[52:55], v[36:39]
	ds_read_b128 v[224:227], v147 offset:42816
	s_waitcnt lgkmcnt(6)
	v_mfma_f32_16x16x32_bf16 v[90:93], v[244:247], v[78:81], 0
	ds_read_b128 v[236:239], v146 offset:58176
	s_waitcnt lgkmcnt(6)
	v_mfma_f32_16x16x32_bf16 v[86:89], v[248:251], v[82:85], v[90:93]
	ds_read_b128 v[244:247], v146 offset:58304
	s_nop 5
	v_mfma_f32_16x16x32_bf16 v[86:89], v[232:235], v[40:43], v[86:89]
	ds_read_b128 v[248:251], v146 offset:58240
	s_waitcnt lgkmcnt(7)
	v_mfma_f32_16x16x32_bf16 v[86:89], v[252:255], v[44:47], v[86:89]
	ds_read_b128 v[232:235], v147 offset:17408
	s_waitcnt lgkmcnt(7)
	v_mfma_f32_16x16x32_bf16 v[86:89], v[216:219], v[48:51], v[86:89]
	ds_read_b128 v[252:255], v120
	s_waitcnt lgkmcnt(7)
	v_mfma_f32_16x16x32_bf16 v[86:89], v[228:231], v[52:55], v[86:89]
	ds_read_b128 v[216:219], v147 offset:17472
	ds_read_b128 v[198:201], v146 offset:58112
	s_waitcnt lgkmcnt(8)
	v_mfma_f32_16x16x32_bf16 v[78:81], v[220:223], v[78:81], 0
	ds_read_b128 v[228:231], v120 offset:64
	v_lshlrev_b32_e32 v94, 1, v56
	v_subrev_u32_e32 v96, 63, v94
	v_cndmask_b32_e32 v56, v148, v149, vcc
	s_waitcnt lgkmcnt(8)
	v_mfma_f32_16x16x32_bf16 v[78:81], v[224:227], v[82:85], v[78:81]
	ds_read_b128 v[220:223], v147 offset:19712
	v_or_b32_e32 v90, 1, v94
	v_ashrrev_i32_e32 v91, 31, v90
	s_waitcnt lgkmcnt(2)
	v_mfma_f32_16x16x32_bf16 v[40:43], v[198:201], v[40:43], v[78:81]
	v_cndmask_b32_e32 v95, 0, v91, vcc
	v_cndmask_b32_e32 v94, v96, v90, vcc
	s_nop 0
	v_mfma_f32_16x16x32_bf16 v[40:43], v[236:239], v[44:47], v[40:43]
	ds_read_b128 v[224:227], v147 offset:19776
	v_lshl_add_u64 v[44:45], s[94:95], 0, v[56:57]
	v_lshlrev_b64 v[46:47], 20, v[94:95]
	v_lshl_add_u64 v[94:95], v[44:45], 0, v[46:47]
	v_mfma_f32_16x16x32_bf16 v[40:43], v[248:251], v[48:51], v[40:43]
	ds_read_b128 v[236:239], v147 offset:22016
	v_and_b32_e32 v44, 0x7fc00, v164
	v_lshlrev_b32_e32 v56, 1, v44
	v_cvt_pk_bf16_f32 v96, v32, v33
	v_mfma_f32_16x16x32_bf16 v[40:43], v[244:247], v[52:55], v[40:43]
	ds_read_b128 v[248:251], v120 offset:128
	ds_read_b128 v[52:55], v77 offset:35840
	ds_read_b128 v[78:81], v77 offset:35904
	v_pk_mul_f32 v[0:1], v[0:1], v[252:253]
	ds_read_b128 v[244:247], v147 offset:22080
	v_pk_mul_f32 v[2:3], v[2:3], v[254:255]
	v_cvt_pk_bf16_f32 v97, v34, v35
	s_waitcnt lgkmcnt(2)
	v_mfma_f32_16x16x32_bf16 v[0:3], v[232:235], v[52:55], v[0:3]
	ds_read_b128 v[252:255], v147 offset:24320
	v_pk_mul_f32 v[4:5], v[4:5], v[228:229]
	ds_read_b128 v[232:235], v147 offset:24384
	v_pk_mul_f32 v[6:7], v[6:7], v[230:231]
	s_waitcnt lgkmcnt(3)
	v_mfma_f32_16x16x32_bf16 v[0:3], v[216:219], v[78:81], v[0:3]
	ds_read_b128 v[228:231], v147 offset:26624
	v_lshl_add_u64 v[94:95], v[94:95], 0, v[56:57]
	v_mov_b32_e32 v77, v57
	v_lshl_add_u64 v[94:95], v[94:95], 0, v[76:77]
	v_mfma_f32_16x16x32_bf16 v[4:7], v[220:223], v[52:55], v[4:7]
	ds_read_b128 v[216:219], v120 offset:256
	v_lshl_add_u64 v[94:95], v[58:59], 1, v[94:95]
	v_lshlrev_b32_e32 v56, 1, v112
	v_mfma_f32_16x16x32_bf16 v[4:7], v[224:227], v[78:81], v[4:7]
	ds_read_b128 v[220:223], v147 offset:26688
	ds_read_b128 v[90:93], v120 offset:192
	v_pk_mul_f32 v[12:13], v[12:13], v[248:249]
	ds_read_b128 v[224:227], v120 offset:320
	v_pk_mul_f32 v[14:15], v[14:15], v[250:251]
	v_lshl_add_u64 v[94:95], v[94:95], 0, v[56:57]
	s_nop 0
	v_mfma_f32_16x16x32_bf16 v[12:15], v[236:239], v[52:55], v[12:15]
	ds_read_b128 v[248:251], v147 offset:28992
	s_waitcnt lgkmcnt(2)
	v_pk_mul_f32 v[8:9], v[8:9], v[90:91]
	v_pk_mul_f32 v[10:11], v[10:11], v[92:93]
	v_mfma_f32_16x16x32_bf16 v[12:15], v[244:247], v[78:81], v[12:15]
	ds_read_b128 v[236:239], v147 offset:31232
	v_cvt_pk_bf16_f32 v90, v36, v37
	v_cvt_pk_bf16_f32 v91, v38, v39
	v_cmp_eq_u32_e32 vcc, -2, v74
	v_mfma_f32_16x16x32_bf16 v[8:11], v[252:255], v[52:55], v[8:11]
	ds_read_b128 v[244:247], v120 offset:384
	v_add_u32_e32 v164, 0xffff0000, v164
	s_or_b64 s[52:53], vcc, s[52:53]
	v_mfma_f32_16x16x32_bf16 v[8:11], v[232:235], v[78:81], v[8:11]
	v_pk_mul_f32 v[20:21], v[20:21], v[216:217]
	v_pk_mul_f32 v[22:23], v[22:23], v[218:219]
	ds_read_b128 v[82:85], v147 offset:28928
	global_store_dwordx2 v[94:95], v[96:97], off
	v_mfma_f32_16x16x32_bf16 v[20:23], v[228:231], v[52:55], v[20:23]
	s_waitcnt lgkmcnt(4)
	v_pk_mul_f32 v[16:17], v[16:17], v[224:225]
	v_pk_mul_f32 v[18:19], v[18:19], v[226:227]
	v_mfma_f32_16x16x32_bf16 v[20:23], v[220:223], v[78:81], v[20:23]
	global_store_dwordx2 v[94:95], v[90:91], off offset:32
	s_waitcnt lgkmcnt(1)
	v_pk_mul_f32 v[28:29], v[28:29], v[244:245]
	s_waitcnt lgkmcnt(0)
	v_mfma_f32_16x16x32_bf16 v[16:19], v[82:85], v[52:55], v[16:19]
	v_mul_f32_e64 v30, v30, v246
	v_mul_f32_e64 v31, v31, v247
	v_cvt_pk_bf16_f32 v82, v86, v87
	v_cvt_pk_bf16_f32 v83, v88, v89
	v_mfma_f32_16x16x32_bf16 v[16:19], v[248:251], v[78:81], v[16:19]
	ds_read_b128 v[44:47], v147 offset:31296
	ds_read_b128 v[48:51], v120 offset:448
	ds_read_b128 v[36:39], v147 offset:33536
	global_store_dwordx2 v[94:95], v[82:83], off offset:64
	v_mfma_f32_16x16x32_bf16 v[28:31], v[236:239], v[52:55], v[28:31]
	ds_read_b128 v[32:35], v147 offset:33600
	s_waitcnt lgkmcnt(2)
	v_pk_mul_f32 v[24:25], v[24:25], v[48:49]
	v_pk_mul_f32 v[26:27], v[26:27], v[50:51]
	v_mfma_f32_16x16x32_bf16 v[28:31], v[44:47], v[78:81], v[28:31]
	s_nop 0
	s_waitcnt lgkmcnt(1)
	v_mfma_f32_16x16x32_bf16 v[24:27], v[36:39], v[52:55], v[24:27]
	v_cvt_pk_bf16_f32 v36, v40, v41
	v_cvt_pk_bf16_f32 v37, v42, v43
	global_store_dwordx2 v[94:95], v[36:37], off offset:96
	s_waitcnt lgkmcnt(0)
	v_mfma_f32_16x16x32_bf16 v[24:27], v[32:35], v[78:81], v[24:27]
	s_barrier
	s_andn2_b64 exec, exec, s[52:53]
	s_cbranch_execz .LBB0_1498

.LBB0_1506:
	s_or_b64 exec, exec, s[58:59]
	v_sub_f32_e32 v32, v156, v33
	v_exp_f32_e32 v156, v32
	v_sub_f32_e32 v32, v157, v35
	v_exp_f32_e32 v158, v32
	v_mov_b32_e32 v32, v36
	v_mov_b32_e32 v33, v38
	v_mov_b32_e32 v38, v37
	v_pk_mul_f32 v[32:33], v[156:157], v[32:33] op_sel_hi:[0,1]
	v_pk_mul_f32 v[34:35], v[158:159], v[38:39] op_sel_hi:[0,1]
	v_cvt_pk_bf16_f32 v36, v32, v33
	v_cvt_pk_bf16_f32 v32, v34, v35
	v_mov_b32_e32 v34, v40
	v_mov_b32_e32 v35, v42
	v_pk_mul_f32 v[34:35], v[156:157], v[34:35] op_sel_hi:[0,1]
	v_mov_b32_e32 v42, v41
	v_cvt_pk_bf16_f32 v37, v34, v35
	v_mov_b32_e32 v34, v44
	v_mov_b32_e32 v35, v46
	v_mov_b32_e32 v46, v45
	v_pk_mul_f32 v[38:39], v[158:159], v[42:43] op_sel_hi:[0,1]
	v_pk_mul_f32 v[34:35], v[156:157], v[34:35] op_sel_hi:[0,1]
	v_pk_mul_f32 v[40:41], v[158:159], v[46:47] op_sel_hi:[0,1]
	v_cvt_pk_bf16_f32 v33, v38, v39
	v_cvt_pk_bf16_f32 v38, v34, v35
	v_cvt_pk_bf16_f32 v34, v40, v41
	v_mov_b32_e32 v40, v48
	v_mov_b32_e32 v41, v50
	v_pk_mul_f32 v[40:41], v[156:157], v[40:41] op_sel_hi:[0,1]
	v_mov_b32_e32 v50, v49
	v_pk_mul_f32 v[42:43], v[158:159], v[50:51] op_sel_hi:[0,1]
	v_cvt_pk_bf16_f32 v39, v40, v41
	v_mov_b32_e32 v40, v52
	v_mov_b32_e32 v41, v54
	v_mov_b32_e32 v54, v53
	v_cvt_pk_bf16_f32 v35, v42, v43
	v_pk_mul_f32 v[40:41], v[156:157], v[40:41] op_sel_hi:[0,1]
	v_pk_mul_f32 v[42:43], v[158:159], v[54:55] op_sel_hi:[0,1]
	v_cvt_pk_bf16_f32 v44, v40, v41
	v_cvt_pk_bf16_f32 v40, v42, v43
	v_mov_b32_e32 v42, v56
	v_mov_b32_e32 v43, v60
	v_pk_mul_f32 v[42:43], v[156:157], v[42:43] op_sel_hi:[0,1]
	v_mov_b32_e32 v60, v57
	v_cvt_pk_bf16_f32 v45, v42, v43
	v_mov_b32_e32 v42, v86
	v_mov_b32_e32 v43, v88
	v_mov_b32_e32 v88, v87
	v_pk_mul_f32 v[46:47], v[158:159], v[60:61] op_sel_hi:[0,1]
	v_pk_mul_f32 v[42:43], v[156:157], v[42:43] op_sel_hi:[0,1]
	v_pk_mul_f32 v[48:49], v[158:159], v[88:89] op_sel_hi:[0,1]
	v_cvt_pk_bf16_f32 v41, v46, v47
	v_cvt_pk_bf16_f32 v46, v42, v43
	v_cvt_pk_bf16_f32 v42, v48, v49
	v_mov_b32_e32 v48, v62
	v_mov_b32_e32 v49, v58
	v_mov_b32_e32 v58, v63
	v_pk_mul_f32 v[48:49], v[156:157], v[48:49] op_sel_hi:[0,1]
	v_pk_mul_f32 v[50:51], v[158:159], v[58:59] op_sel_hi:[0,1]
	v_cvt_pk_bf16_f32 v47, v48, v49
	v_cvt_pk_bf16_f32 v43, v50, v51
	s_waitcnt lgkmcnt(0)
	s_barrier
	s_waitcnt lgkmcnt(0)
	ds_read_b128 v[216:219], v114
	v_add_u32_e32 v52, v115, v117
	v_add_u32_e32 v60, v115, v113
	v_cmp_eq_u32_e32 vcc, s74, v133
	v_lshl_add_u64 v[80:81], v[80:81], 0, s[54:55]
	s_waitcnt lgkmcnt(0)
	v_pk_mul_f32 v[48:49], v[12:13], v[216:217]
	v_pk_mul_f32 v[50:51], v[14:15], v[218:219]
	v_cvt_pk_bf16_f32 v48, v48, v49
	v_cvt_pk_bf16_f32 v49, v50, v51
	ds_write_b64 v52, v[48:49] offset:45056
	ds_read_b128 v[220:223], v114 offset:64
	v_lshl_add_u64 v[82:83], v[82:83], 0, s[54:55]
	v_lshl_add_u64 v[84:85], v[84:85], 0, s[54:55]
	s_or_b64 s[56:57], vcc, s[56:57]
	s_waitcnt lgkmcnt(0)
	v_pk_mul_f32 v[48:49], v[0:1], v[220:221]
	v_pk_mul_f32 v[50:51], v[2:3], v[222:223]
	v_cvt_pk_bf16_f32 v48, v48, v49
	v_cvt_pk_bf16_f32 v49, v50, v51
	ds_write_b64 v91, v[48:49] offset:45056
	ds_read_b128 v[224:227], v114 offset:128
	s_waitcnt lgkmcnt(0)
	v_pk_mul_f32 v[48:49], v[8:9], v[224:225]
	v_pk_mul_f32 v[50:51], v[10:11], v[226:227]
	v_cvt_pk_bf16_f32 v48, v48, v49
	v_cvt_pk_bf16_f32 v49, v50, v51
	ds_write_b64 v92, v[48:49] offset:45056
	ds_read_b128 v[228:231], v114 offset:192
	s_waitcnt lgkmcnt(0)
	v_pk_mul_f32 v[48:49], v[4:5], v[228:229]
	v_pk_mul_f32 v[50:51], v[6:7], v[230:231]
	v_cvt_pk_bf16_f32 v48, v48, v49
	v_cvt_pk_bf16_f32 v49, v50, v51
	ds_write_b64 v93, v[48:49] offset:45056
	ds_read_b128 v[232:235], v114 offset:256
	s_waitcnt lgkmcnt(0)
	v_pk_mul_f32 v[48:49], v[20:21], v[232:233]
	v_pk_mul_f32 v[50:51], v[22:23], v[234:235]
	v_cvt_pk_bf16_f32 v48, v48, v49
	v_cvt_pk_bf16_f32 v49, v50, v51
	ds_write_b64 v52, v[48:49] offset:45184
	ds_read_b128 v[236:239], v114 offset:320
	s_waitcnt lgkmcnt(0)
	v_pk_mul_f32 v[48:49], v[16:17], v[236:237]
	v_pk_mul_f32 v[50:51], v[18:19], v[238:239]
	v_cvt_pk_bf16_f32 v48, v48, v49
	v_cvt_pk_bf16_f32 v49, v50, v51
	ds_write_b64 v52, v[48:49] offset:45216
	ds_read_b128 v[244:247], v114 offset:384
	s_waitcnt lgkmcnt(0)
	v_pk_mul_f32 v[48:49], v[24:25], v[244:245]
	v_pk_mul_f32 v[50:51], v[26:27], v[246:247]
	v_cvt_pk_bf16_f32 v48, v48, v49
	v_cvt_pk_bf16_f32 v49, v50, v51
	ds_write_b64 v52, v[48:49] offset:45248
	ds_read_b128 v[248:251], v114 offset:448
	s_waitcnt lgkmcnt(0)
	v_pk_mul_f32 v[48:49], v[28:29], v[248:249]
	v_pk_mul_f32 v[50:51], v[30:31], v[250:251]
	v_cvt_pk_bf16_f32 v48, v48, v49
	v_cvt_pk_bf16_f32 v49, v50, v51
	ds_write_b64 v52, v[48:49] offset:45280
	ds_read_b128 v[252:255], v94 offset:17408
	ds_read_b128 v[216:219], v94 offset:17472
	ds_read_b128 v[220:223], v94 offset:21824
	ds_read_b128 v[224:227], v94 offset:17536
	ds_read_b128 v[228:231], v94 offset:17600
	ds_read_b128 v[232:235], v94 offset:21760
	ds_read_b128 v[236:239], v94 offset:21888
	ds_read_b128 v[244:247], v94 offset:21952
	ds_read_b128 v[48:51], v60
	ds_read_b128 v[52:55], v60 offset:64
	ds_read_b128 v[56:59], v60 offset:128
	ds_read_b128 v[60:63], v60 offset:192
	s_waitcnt lgkmcnt(3)
	v_mfma_f32_16x16x32_bf16 v[86:89], v[252:255], v[48:51], 0
	ds_read_b128 v[248:251], v94 offset:26176
	s_waitcnt lgkmcnt(3)
	v_mfma_f32_16x16x32_bf16 v[86:89], v[216:219], v[52:55], v[86:89]
	ds_read_b128 v[252:255], v94 offset:26112
	s_waitcnt lgkmcnt(3)
	v_mfma_f32_16x16x32_bf16 v[86:89], v[224:227], v[56:59], v[86:89]
	ds_read_b128 v[216:219], v94 offset:26240
	s_waitcnt lgkmcnt(3)
	v_mfma_f32_16x16x32_bf16 v[86:89], v[228:231], v[60:63], v[86:89]
	ds_read_b128 v[224:227], v94 offset:26304
	s_nop 6
	v_cndmask_b32_e64 v86, v86, 0, s[6:7]
	v_mfma_f32_16x16x32_bf16 v[156:159], v[232:235], v[48:51], 0
	ds_read_b128 v[228:231], v94 offset:30528
	v_cndmask_b32_e64 v87, 0, v87, s[8:9]
	v_cndmask_b32_e64 v88, v88, 0, s[10:11]
	v_cndmask_b32_e64 v89, v89, 0, s[12:13]
	v_mfma_f32_16x16x32_bf16 v[156:159], v[220:223], v[52:55], v[156:159]
	ds_read_b128 v[232:235], v94 offset:30464
	v_cvt_pk_bf16_f32 v86, v86, v87
	v_cvt_pk_bf16_f32 v87, v88, v89
	v_mfma_f32_16x16x32_bf16 v[156:159], v[236:239], v[56:59], v[156:159]
	ds_read_b128 v[220:223], v94 offset:30592
	v_mfma_f32_16x16x32_bf16 v[156:159], v[244:247], v[60:63], v[156:159]
	s_nop 6
	s_nop 0
	v_cndmask_b32_e64 v88, v156, 0, s[14:15]
	v_cndmask_b32_e64 v89, v157, 0, s[16:17]
	v_cndmask_b32_e64 v156, v158, 0, s[18:19]
	v_cndmask_b32_e64 v157, v159, 0, s[20:21]
	v_cvt_pk_bf16_f32 v88, v88, v89
	v_cvt_pk_bf16_f32 v89, v156, v157
	s_waitcnt lgkmcnt(5)
	v_mfma_f32_16x16x32_bf16 v[156:159], v[252:255], v[48:51], 0
	v_mfma_f32_16x16x32_bf16 v[156:159], v[248:251], v[52:55], v[156:159]
	s_waitcnt lgkmcnt(4)
	v_mfma_f32_16x16x32_bf16 v[156:159], v[216:219], v[56:59], v[156:159]
	s_waitcnt lgkmcnt(3)
	v_mfma_f32_16x16x32_bf16 v[156:159], v[224:227], v[60:63], v[156:159]
	s_nop 6
	s_nop 0
	v_cndmask_b32_e64 v156, v156, 0, s[22:23]
	v_cndmask_b32_e64 v157, v157, 0, s[24:25]
	v_cndmask_b32_e64 v158, v158, 0, s[26:27]
	v_cndmask_b32_e64 v159, v159, 0, s[28:29]
	v_cvt_pk_bf16_f32 v164, v156, v157
	v_cvt_pk_bf16_f32 v165, v158, v159
	s_waitcnt lgkmcnt(1)
	v_mfma_f32_16x16x32_bf16 v[156:159], v[232:235], v[48:51], 0
	v_mfma_f32_16x16x32_bf16 v[156:159], v[228:231], v[52:55], v[156:159]
	s_waitcnt lgkmcnt(0)
	v_mfma_f32_16x16x32_bf16 v[156:159], v[220:223], v[56:59], v[156:159]
	ds_read_b128 v[160:163], v94 offset:30656
	s_waitcnt lgkmcnt(0)
	s_barrier
	v_mfma_f32_16x16x32_bf16 v[156:159], v[160:163], v[60:63], v[156:159]
	s_nop 7
	v_cndmask_b32_e64 v156, v156, 0, s[30:31]
	v_cndmask_b32_e64 v157, v157, 0, s[34:35]
	v_cndmask_b32_e64 v158, v158, 0, s[36:37]
	v_cndmask_b32_e64 v159, v159, 0, s[38:39]
	v_cvt_pk_bf16_f32 v156, v156, v157
	v_cvt_pk_bf16_f32 v157, v158, v159
	v_add_u32_e32 v158, v116, v117
	v_add_u32_e32 v158, 0xf000, v158
	ds_write2_b64 v158, v[86:87], v[88:89] offset0:128 offset1:132
	ds_write2_b64 v158, v[164:165], v[156:157] offset0:136 offset1:140
	v_add_u32_e32 v86, v118, v119
	ds_write_b128 v86, v[36:39] offset:17408
	ds_write_b128 v86, v[44:47] offset:17424
	ds_write_b128 v86, v[32:35] offset:17552
	ds_write_b128 v86, v[40:43] offset:17568
	v_add_u32_e32 v46, v116, v113
	s_waitcnt lgkmcnt(0)
	s_barrier
	s_waitcnt lgkmcnt(0)
	ds_read_b128 v[216:219], v46 offset:62464
	ds_read_b128 v[220:223], v46 offset:62528
	ds_read_b128 v[224:227], v95 offset:35840
	ds_read_b128 v[228:231], v95 offset:35904
	ds_read_b128 v[232:235], v94 offset:45056
	ds_read_b128 v[236:239], v94 offset:45120
	ds_read_b128 v[244:247], v94 offset:45184
	ds_read_b128 v[248:251], v94 offset:45248
	s_waitcnt lgkmcnt(5)
	v_mfma_f32_16x16x32_bf16 v[42:45], v[224:227], v[216:219], 0
	ds_read_b128 v[252:255], v95 offset:38208
	ds_read_b128 v[224:227], v95 offset:38144
	v_lshlrev_b64 v[32:33], 11, v[70:71]
	v_lshl_add_u64 v[32:33], v[78:79], 0, v[32:33]
	v_add_u32_e32 v70, 64, v70
	s_waitcnt lgkmcnt(6)
	v_mfma_f32_16x16x32_bf16 v[42:45], v[228:231], v[220:223], v[42:45]
	ds_read_b128 v[228:231], v94 offset:49408
	s_waitcnt lgkmcnt(6)
	v_mfma_f32_16x16x32_bf16 v[42:45], v[232:235], v[48:51], v[42:45]
	ds_read_b128 v[232:235], v94 offset:49472
	s_waitcnt lgkmcnt(6)
	v_mfma_f32_16x16x32_bf16 v[42:45], v[236:239], v[52:55], v[42:45]
	ds_read_b128 v[236:239], v94 offset:49536
	s_waitcnt lgkmcnt(6)
	v_mfma_f32_16x16x32_bf16 v[42:45], v[244:247], v[56:59], v[42:45]
	ds_read_b128 v[244:247], v94 offset:49600
	s_waitcnt lgkmcnt(6)
	v_mfma_f32_16x16x32_bf16 v[42:45], v[248:251], v[60:63], v[42:45]
	ds_read_b128 v[248:251], v95 offset:40512
	s_nop 6
	v_cvt_pk_bf16_f32 v42, v42, v43
	v_cvt_pk_bf16_f32 v43, v44, v45
	global_store_dwordx2 v[32:33], v[42:43], off
	s_waitcnt lgkmcnt(5)
	v_mfma_f32_16x16x32_bf16 v[42:45], v[224:227], v[216:219], 0
	ds_read_b128 v[224:227], v95 offset:40448
	v_mfma_f32_16x16x32_bf16 v[42:45], v[252:255], v[220:223], v[42:45]
	ds_read_b128 v[252:255], v94 offset:53760
	s_waitcnt lgkmcnt(6)
	v_mfma_f32_16x16x32_bf16 v[42:45], v[228:231], v[48:51], v[42:45]
	ds_read_b128 v[228:231], v94 offset:53824
	s_waitcnt lgkmcnt(6)
	v_mfma_f32_16x16x32_bf16 v[42:45], v[232:235], v[52:55], v[42:45]
	ds_read_b128 v[232:235], v94 offset:53888
	s_waitcnt lgkmcnt(6)
	v_mfma_f32_16x16x32_bf16 v[42:45], v[236:239], v[56:59], v[42:45]
	ds_read_b128 v[236:239], v95 offset:42752
	s_waitcnt lgkmcnt(6)
	v_mfma_f32_16x16x32_bf16 v[42:45], v[244:247], v[60:63], v[42:45]
	ds_read_b128 v[244:247], v94 offset:58112
	s_nop 6
	v_cvt_pk_bf16_f32 v42, v42, v43
	v_cvt_pk_bf16_f32 v43, v44, v45
	global_store_dwordx2 v[32:33], v[42:43], off offset:32
	s_waitcnt lgkmcnt(5)
	v_mfma_f32_16x16x32_bf16 v[42:45], v[224:227], v[216:219], 0
	ds_read_b128 v[224:227], v94 offset:58176
	v_mfma_f32_16x16x32_bf16 v[42:45], v[248:251], v[220:223], v[42:45]
	ds_read_b128 v[248:251], v94 offset:58240
	s_waitcnt lgkmcnt(6)
	v_mfma_f32_16x16x32_bf16 v[42:45], v[252:255], v[48:51], v[42:45]
	ds_read_b128 v[252:255], v94 offset:58304
	s_waitcnt lgkmcnt(6)
	v_mfma_f32_16x16x32_bf16 v[42:45], v[228:231], v[52:55], v[42:45]
	ds_read_b128 v[228:231], v120
	s_waitcnt lgkmcnt(6)
	v_mfma_f32_16x16x32_bf16 v[42:45], v[232:235], v[56:59], v[42:45]
	ds_read_b128 v[232:235], v95 offset:17408
	ds_read_b128 v[86:89], v94 offset:53952
	s_waitcnt lgkmcnt(0)
	v_mfma_f32_16x16x32_bf16 v[42:45], v[86:89], v[60:63], v[42:45]
	s_nop 7
	v_cvt_pk_bf16_f32 v42, v42, v43
	v_cvt_pk_bf16_f32 v43, v44, v45
	global_store_dwordx2 v[32:33], v[42:43], off offset:64
	v_mfma_f32_16x16x32_bf16 v[34:37], v[236:239], v[216:219], 0
	ds_read_b128 v[216:219], v95 offset:17472
	ds_read_b128 v[236:239], v120 offset:64
	ds_read_b128 v[42:45], v95 offset:42816
	s_waitcnt lgkmcnt(0)
	v_mfma_f32_16x16x32_bf16 v[34:37], v[42:45], v[220:223], v[34:37]
	v_mfma_f32_16x16x32_bf16 v[34:37], v[244:247], v[48:51], v[34:37]
	ds_read_b128 v[220:223], v95 offset:19712
	v_mfma_f32_16x16x32_bf16 v[34:37], v[224:227], v[52:55], v[34:37]
	ds_read_b128 v[244:247], v95 offset:19776
	v_mfma_f32_16x16x32_bf16 v[34:37], v[248:251], v[56:59], v[34:37]
	ds_read_b128 v[224:227], v120 offset:128
	v_mfma_f32_16x16x32_bf16 v[34:37], v[252:255], v[60:63], v[34:37]
	ds_read_b128 v[248:251], v95 offset:22016
	s_nop 7
	v_cvt_pk_bf16_f32 v34, v34, v35
	v_cvt_pk_bf16_f32 v35, v36, v37
	global_store_dwordx2 v[32:33], v[34:35], off offset:96
	ds_read_b128 v[36:39], v46 offset:35840
	ds_read_b128 v[32:35], v46 offset:35904
	v_pk_mul_f32 v[12:13], v[12:13], v[228:229]
	ds_read_b128 v[252:255], v95 offset:22080
	v_pk_mul_f32 v[14:15], v[14:15], v[230:231]
	s_waitcnt lgkmcnt(2)
	s_nop 0
	v_mfma_f32_16x16x32_bf16 v[12:15], v[232:235], v[36:39], v[12:15]
	ds_read_b128 v[228:231], v120 offset:192
	s_waitcnt lgkmcnt(2)
	v_mfma_f32_16x16x32_bf16 v[12:15], v[216:219], v[32:35], v[12:15]
	ds_read_b128 v[232:235], v95 offset:24320
	v_pk_mul_f32 v[0:1], v[0:1], v[236:237]
	ds_read_b128 v[216:219], v95 offset:24384
	v_pk_mul_f32 v[2:3], v[2:3], v[238:239]
	s_nop 1
	v_mfma_f32_16x16x32_bf16 v[0:3], v[220:223], v[36:39], v[0:3]
	ds_read_b128 v[236:239], v120 offset:256
	v_mfma_f32_16x16x32_bf16 v[0:3], v[244:247], v[32:35], v[0:3]
	ds_read_b128 v[220:223], v95 offset:26624
	v_pk_mul_f32 v[8:9], v[8:9], v[224:225]
	ds_read_b128 v[244:247], v95 offset:26688
	v_pk_mul_f32 v[10:11], v[10:11], v[226:227]
	s_nop 1
	v_mfma_f32_16x16x32_bf16 v[8:11], v[248:251], v[36:39], v[8:11]
	ds_read_b128 v[224:227], v120 offset:320
	s_waitcnt lgkmcnt(7)
	v_mfma_f32_16x16x32_bf16 v[8:11], v[252:255], v[32:35], v[8:11]
	ds_read_b128 v[248:251], v95 offset:28928
	s_waitcnt lgkmcnt(7)
	v_pk_mul_f32 v[4:5], v[4:5], v[228:229]
	ds_read_b128 v[252:255], v95 offset:28992
	v_pk_mul_f32 v[6:7], v[6:7], v[230:231]
	s_waitcnt lgkmcnt(7)
	s_nop 0
	v_mfma_f32_16x16x32_bf16 v[4:7], v[232:235], v[36:39], v[4:7]
	ds_read_b128 v[228:231], v120 offset:384
	s_waitcnt lgkmcnt(7)
	v_mfma_f32_16x16x32_bf16 v[4:7], v[216:219], v[32:35], v[4:7]
	ds_read_b128 v[232:235], v95 offset:31232
	s_waitcnt lgkmcnt(7)
	v_pk_mul_f32 v[20:21], v[20:21], v[236:237]
	ds_read_b128 v[216:219], v95 offset:31296
	v_pk_mul_f32 v[22:23], v[22:23], v[238:239]
	s_waitcnt lgkmcnt(7)
	s_nop 0
	v_mfma_f32_16x16x32_bf16 v[20:23], v[220:223], v[36:39], v[20:23]
	ds_read_b128 v[236:239], v120 offset:448
	s_waitcnt lgkmcnt(7)
	v_mfma_f32_16x16x32_bf16 v[20:23], v[244:247], v[32:35], v[20:23]
	s_waitcnt lgkmcnt(6)
	v_pk_mul_f32 v[16:17], v[16:17], v[224:225]
	v_pk_mul_f32 v[18:19], v[18:19], v[226:227]
	s_waitcnt lgkmcnt(5)
	s_nop 0
	v_mfma_f32_16x16x32_bf16 v[16:19], v[248:251], v[36:39], v[16:19]
	s_waitcnt lgkmcnt(4)
	v_mfma_f32_16x16x32_bf16 v[16:19], v[252:255], v[32:35], v[16:19]
	s_waitcnt lgkmcnt(3)
	v_pk_mul_f32 v[24:25], v[24:25], v[228:229]
	v_pk_mul_f32 v[26:27], v[26:27], v[230:231]
	s_waitcnt lgkmcnt(2)
	s_nop 0
	v_mfma_f32_16x16x32_bf16 v[24:27], v[232:235], v[36:39], v[24:27]
	s_waitcnt lgkmcnt(1)
	v_mfma_f32_16x16x32_bf16 v[24:27], v[216:219], v[32:35], v[24:27]
	s_waitcnt lgkmcnt(0)
	v_pk_mul_f32 v[28:29], v[28:29], v[236:237]
	v_pk_mul_f32 v[30:31], v[30:31], v[238:239]
	ds_read_b128 v[40:43], v95 offset:33536
	s_waitcnt lgkmcnt(0)
	v_mfma_f32_16x16x32_bf16 v[28:31], v[40:43], v[36:39], v[28:31]
	ds_read_b128 v[36:39], v95 offset:33600
	s_waitcnt lgkmcnt(0)
	s_barrier
	v_mfma_f32_16x16x32_bf16 v[28:31], v[36:39], v[32:35], v[28:31]
	s_andn2_b64 exec, exec, s[56:57]
	s_cbranch_execz .LBB0_1511
